# speedup vs baseline: 1.0194x; 1.0194x over previous
.LBB0_938:
	s_andn2_saveexec_b64 s[52:53], s[52:53]
	s_cbranch_execz .LBB0_958
	v_readfirstlane_b32 s34, v136
	s_nop 3
	s_cmp_eq_u32 s34, 0
	s_cbranch_scc1 .Lcv_nodrain
	s_waitcnt vmcnt(0)
	s_cmp_eq_u32 s34, 1
	s_cbranch_scc1 .Lcv_noscale
	v_readlane_b32 s98, v197, 0
	v_readlane_b32 s99, v197, 1
	v_readlane_b32 s100, v197, 2
	v_readlane_b32 s101, v197, 3
	v_mul_f32_e32 v96, s98, v96
	v_mul_f32_e32 v97, s99, v97
	v_mul_f32_e32 v34, s100, v34
	v_mul_f32_e32 v35, s101, v35
	v_readlane_b32 s98, v197, 4
	v_readlane_b32 s99, v197, 5
	v_readlane_b32 s100, v197, 6
	v_readlane_b32 s101, v197, 7
	v_mul_f32_e32 v98, s98, v98
	v_mul_f32_e32 v99, s99, v99
	v_mul_f32_e32 v40, s100, v40
	v_mul_f32_e32 v41, s101, v41
	v_readlane_b32 s98, v197, 8
	v_readlane_b32 s99, v197, 9
	v_readlane_b32 s100, v197, 10
	v_readlane_b32 s101, v197, 11
	v_mul_f32_e32 v94, s98, v94
	v_mul_f32_e32 v95, s99, v95
	v_mul_f32_e32 v38, s100, v38
	v_mul_f32_e32 v39, s101, v39
	v_readlane_b32 s98, v197, 12
	v_readlane_b32 s99, v197, 13
	v_readlane_b32 s100, v197, 14
	v_readlane_b32 s101, v197, 15
	v_mul_f32_e32 v42, s98, v42
	v_mul_f32_e32 v43, s99, v43
	v_mul_f32_e32 v46, s100, v46
	v_mul_f32_e32 v47, s101, v47
	v_readlane_b32 s98, v197, 16
	v_readlane_b32 s99, v197, 17
	v_readlane_b32 s100, v197, 18
	v_readlane_b32 s101, v197, 19
	v_mul_f32_e32 v44, s98, v44
	v_mul_f32_e32 v45, s99, v45
	v_mul_f32_e32 v48, s100, v48
	v_mul_f32_e32 v49, s101, v49
	v_readlane_b32 s98, v197, 20
	v_readlane_b32 s99, v197, 21
	v_readlane_b32 s100, v197, 22
	v_readlane_b32 s101, v197, 23
	v_mul_f32_e32 v50, s98, v50
	v_mul_f32_e32 v51, s99, v51
	v_mul_f32_e32 v54, s100, v54
	v_mul_f32_e32 v55, s101, v55
	v_readlane_b32 s98, v197, 24
	v_readlane_b32 s99, v197, 25
	v_readlane_b32 s100, v197, 26
	v_readlane_b32 s101, v197, 27
	v_mul_f32_e32 v52, s98, v52
	v_mul_f32_e32 v53, s99, v53
	v_mul_f32_e32 v56, s100, v56
	v_mul_f32_e32 v57, s101, v57
	v_readlane_b32 s98, v197, 28
	v_readlane_b32 s99, v197, 29
	v_readlane_b32 s100, v197, 30
	v_readlane_b32 s101, v197, 31
	v_mul_f32_e32 v58, s98, v58
	v_mul_f32_e32 v59, s99, v59
	v_mul_f32_e32 v62, s100, v62
	v_mul_f32_e32 v63, s101, v63
	v_readlane_b32 s98, v197, 32
	v_readlane_b32 s99, v197, 33
	v_readlane_b32 s100, v197, 34
	v_readlane_b32 s101, v197, 35
	v_mul_f32_e32 v60, s98, v60
	v_mul_f32_e32 v61, s99, v61
	v_mul_f32_e32 v64, s100, v64
	v_mul_f32_e32 v65, s101, v65
	v_readlane_b32 s98, v197, 36
	v_readlane_b32 s99, v197, 37
	v_readlane_b32 s100, v197, 38
	v_readlane_b32 s101, v197, 39
	v_mul_f32_e32 v66, s98, v66
	v_mul_f32_e32 v67, s99, v67
	v_mul_f32_e32 v70, s100, v70
	v_mul_f32_e32 v71, s101, v71
	v_readlane_b32 s98, v197, 40
	v_readlane_b32 s99, v197, 41
	v_readlane_b32 s100, v197, 42
	v_readlane_b32 s101, v197, 43
	v_mul_f32_e32 v68, s98, v68
	v_mul_f32_e32 v69, s99, v69
	v_mul_f32_e32 v72, s100, v72
	v_mul_f32_e32 v73, s101, v73
	v_readlane_b32 s98, v197, 44
	v_readlane_b32 s99, v197, 45
	v_readlane_b32 s100, v197, 46
	v_readlane_b32 s101, v197, 47
	v_mul_f32_e32 v74, s98, v74
	v_mul_f32_e32 v75, s99, v75
	v_mul_f32_e32 v78, s100, v78
	v_mul_f32_e32 v79, s101, v79
	v_readlane_b32 s98, v197, 48
	v_readlane_b32 s99, v197, 49
	v_readlane_b32 s100, v197, 50
	v_readlane_b32 s101, v197, 51
	v_mul_f32_e32 v76, s98, v76
	v_mul_f32_e32 v77, s99, v77
	v_mul_f32_e32 v80, s100, v80
	v_mul_f32_e32 v81, s101, v81
	v_readlane_b32 s98, v197, 52
	v_readlane_b32 s99, v197, 53
	v_readlane_b32 s100, v197, 54
	v_readlane_b32 s101, v197, 55
	v_mul_f32_e32 v82, s98, v82
	v_mul_f32_e32 v83, s99, v83
	v_mul_f32_e32 v86, s100, v86
	v_mul_f32_e32 v87, s101, v87
	v_readlane_b32 s98, v197, 56
	v_readlane_b32 s99, v197, 57
	v_readlane_b32 s100, v197, 58
	v_readlane_b32 s101, v197, 59
	v_mul_f32_e32 v84, s98, v84
	v_mul_f32_e32 v85, s99, v85
	v_mul_f32_e32 v88, s100, v88
	v_mul_f32_e32 v89, s101, v89
	v_readlane_b32 s98, v197, 60
	v_readlane_b32 s99, v197, 61
	v_readlane_b32 s100, v197, 62
	v_readlane_b32 s101, v197, 63
	v_mul_f32_e32 v90, s98, v90
	v_mul_f32_e32 v91, s99, v91
	v_mul_f32_e32 v92, s100, v92
	v_mul_f32_e32 v93, s101, v93
.Lcv_noscale:
	v_cvt_pk_bf16_f32 v16, v96, v97
	v_cvt_pk_bf16_f32 v17, v34, v35
	v_cvt_pk_bf16_f32 v18, v98, v99
	v_cvt_pk_bf16_f32 v19, v40, v41
	global_store_dwordx4 v[100:101], v[16:19], off
	s_nop 1
	v_cvt_pk_bf16_f32 v16, v94, v95
	v_cvt_pk_bf16_f32 v17, v38, v39
	v_cvt_pk_bf16_f32 v18, v42, v43
	v_cvt_pk_bf16_f32 v19, v46, v47
	global_store_dwordx4 v[100:101], v[16:19], off offset:16
	s_nop 1
	v_cvt_pk_bf16_f32 v16, v44, v45
	v_cvt_pk_bf16_f32 v17, v48, v49
	v_cvt_pk_bf16_f32 v18, v50, v51
	v_cvt_pk_bf16_f32 v19, v54, v55
	global_store_dwordx4 v[100:101], v[16:19], off offset:32
	s_nop 1
	v_cvt_pk_bf16_f32 v16, v52, v53
	v_cvt_pk_bf16_f32 v17, v56, v57
	v_cvt_pk_bf16_f32 v18, v58, v59
	v_cvt_pk_bf16_f32 v19, v62, v63
	global_store_dwordx4 v[100:101], v[16:19], off offset:48
	s_nop 1
	v_cvt_pk_bf16_f32 v16, v60, v61
	v_cvt_pk_bf16_f32 v17, v64, v65
	v_cvt_pk_bf16_f32 v18, v66, v67
	v_cvt_pk_bf16_f32 v19, v70, v71
	global_store_dwordx4 v[100:101], v[16:19], off offset:64
	s_nop 1
	v_cvt_pk_bf16_f32 v16, v68, v69
	v_cvt_pk_bf16_f32 v17, v72, v73
	v_cvt_pk_bf16_f32 v18, v74, v75
	v_cvt_pk_bf16_f32 v19, v78, v79
	global_store_dwordx4 v[100:101], v[16:19], off offset:80
	s_nop 1
	v_cvt_pk_bf16_f32 v16, v76, v77
	v_cvt_pk_bf16_f32 v17, v80, v81
	v_cvt_pk_bf16_f32 v18, v82, v83
	v_cvt_pk_bf16_f32 v19, v86, v87
	global_store_dwordx4 v[100:101], v[16:19], off offset:96
	s_nop 1
	v_cvt_pk_bf16_f32 v16, v84, v85
	v_cvt_pk_bf16_f32 v17, v88, v89
	v_cvt_pk_bf16_f32 v18, v90, v91
	v_cvt_pk_bf16_f32 v19, v92, v93
	global_store_dwordx4 v[100:101], v[16:19], off offset:112
	s_nop 1
	v_mov_b32_e32 v136, 0
.Lcv_nodrain:
	s_mov_b32 s34, 0xa800
	v_cmp_gt_i32_e64 s[34:35], s34, v102
	s_and_saveexec_b64 s[54:55], s[34:35]
	s_cbranch_execz .LBB0_957
	s_mov_b64 s[72:73], s[10:11]
	v_readlane_b32 s8, v249, 14
	v_readlane_b32 s9, v249, 15
	v_readlane_b32 s10, v249, 16
	v_readlane_b32 s11, v249, 17
	s_movk_i32 s34, 0x3fff
	v_cmp_lt_i32_e64 s[34:35], s34, v102
	v_mov_b64_e32 v[16:17], s[10:11]
	v_readlane_b32 s8, v252, 37
	v_readlane_b32 s9, v252, 38
	v_mov_b64_e32 v[20:21], 0
	v_mov_b64_e32 v[96:97], 0x4000
	v_mov_b64_e32 v[94:95], s[8:9]
	v_mov_b32_e32 v18, v102
	v_readlane_b32 s10, v252, 39
	v_readlane_b32 s11, v252, 40
	v_readlane_b32 s12, v252, 41
	v_readlane_b32 s13, v252, 42
	v_readlane_b32 s14, v252, 43
	v_readlane_b32 s15, v252, 44
	v_readlane_b32 s16, v252, 45
	v_readlane_b32 s17, v252, 46
	v_readlane_b32 s18, v252, 47
	v_readlane_b32 s19, v252, 48
	v_readlane_b32 s20, v252, 49
	v_readlane_b32 s21, v252, 50
	v_readlane_b32 s22, v252, 51
	v_readlane_b32 s23, v252, 52
	s_and_saveexec_b64 s[56:57], s[34:35]
	s_cbranch_execz .LBB0_954
	v_readlane_b32 s8, v252, 53
	s_movk_i32 s34, 0x4fff
	v_readlane_b32 s16, v252, 61
	v_readlane_b32 s17, v252, 62
	v_cmp_lt_u32_e64 s[34:35], s34, v102
	v_readlane_b32 s9, v252, 54
	v_mov_b64_e32 v[94:95], s[16:17]
	v_readlane_b32 s10, v252, 55
	v_readlane_b32 s11, v252, 56
	v_readlane_b32 s12, v252, 57
	v_readlane_b32 s13, v252, 58
	v_readlane_b32 s14, v252, 59
	v_readlane_b32 s15, v252, 60
	v_readlane_b32 s18, v252, 63
	v_readlane_b32 s19, v249, 0
	v_readlane_b32 s20, v249, 1
	v_readlane_b32 s21, v249, 2
	v_readlane_b32 s22, v249, 3
	v_readlane_b32 s23, v249, 4
	s_and_saveexec_b64 s[58:59], s[34:35]
	s_xor_b64 s[58:59], exec, s[58:59]
	s_cbranch_execz .LBB0_951
	v_readlane_b32 s8, v252, 53
	s_movk_i32 s34, 0x57ff
	v_readlane_b32 s18, v252, 63
	v_readlane_b32 s19, v249, 0
	v_readlane_b32 s20, v249, 1
	v_readlane_b32 s21, v249, 2
	v_cmp_lt_u32_e64 s[34:35], s34, v102
	v_mov_b64_e32 v[20:21], s[18:19]
	v_mov_b64_e32 v[94:95], s[20:21]
	v_readlane_b32 s9, v252, 54
	v_readlane_b32 s10, v252, 55
	v_readlane_b32 s11, v252, 56
	v_readlane_b32 s12, v252, 57
	v_readlane_b32 s13, v252, 58
	v_readlane_b32 s14, v252, 59
	v_readlane_b32 s15, v252, 60
	v_readlane_b32 s16, v252, 61
	v_readlane_b32 s17, v252, 62
	v_readlane_b32 s22, v249, 3
	v_readlane_b32 s23, v249, 4
	s_and_saveexec_b64 s[60:61], s[34:35]
	s_xor_b64 s[60:61], exec, s[60:61]
	s_cbranch_execz .LBB0_948
	s_mov_b32 s11, s39
	s_mov_b32 s10, s41
	v_readlane_b32 s36, v252, 0
	s_mov_b32 s34, 0x97ff
	v_readlane_b32 s37, v252, 1
	v_readlane_b32 s38, v252, 2
	v_readlane_b32 s39, v252, 3
	v_cmp_lt_u32_e64 s[34:35], s34, v102
	v_mov_b64_e32 v[20:21], s[36:37]
	v_mov_b64_e32 v[94:95], s[38:39]
	v_readlane_b32 s40, v252, 4
	v_readlane_b32 s41, v252, 5
	v_readlane_b32 s42, v252, 6
	v_readlane_b32 s43, v252, 7
	s_and_saveexec_b64 s[64:65], s[34:35]
	s_xor_b64 s[34:35], exec, s[64:65]
	s_cbranch_execz .LBB0_945
	v_readlane_b32 s36, v252, 0
	v_readlane_b32 s42, v252, 6
	v_readlane_b32 s43, v252, 7
	v_add_u32_e32 v18, 0xffff6800, v102
	v_mov_b64_e32 v[20:21], 0
	v_readlane_b32 s37, v252, 1
	v_readlane_b32 s38, v252, 2
	v_readlane_b32 s39, v252, 3
	v_readlane_b32 s40, v252, 4
	v_readlane_b32 s41, v252, 5
	v_mov_b64_e32 v[94:95], s[42:43]
.LBB0_945:
	s_or_saveexec_b64 s[34:35], s[34:35]
	v_readlane_b32 s8, v249, 20
	v_readlane_b32 s9, v249, 21
	v_mov_b64_e32 v[96:97], 0x1000
	s_nop 0
	v_mov_b64_e32 v[16:17], s[8:9]
	s_xor_b64 exec, exec, s[34:35]
	s_cbranch_execz .LBB0_947
	v_readlane_b32 s8, v249, 22
	v_readlane_b32 s9, v249, 23
	v_add_u32_e32 v18, 0xffffa800, v102
	v_mov_b64_e32 v[96:97], 0x4000
	v_mov_b64_e32 v[16:17], s[8:9]

.LBB0_948:
	s_andn2_saveexec_b64 s[34:35], s[60:61]
	s_cbranch_execz .LBB0_950
	v_readlane_b32 s8, v249, 24
	v_readlane_b32 s9, v249, 25
	v_add_u32_e32 v18, 0xffffb000, v102
	v_mov_b64_e32 v[96:97], 0x800
	v_mov_b64_e32 v[16:17], s[8:9]

.LBB0_951:
	s_andn2_saveexec_b64 s[34:35], s[58:59]
	s_cbranch_execz .LBB0_953
	v_readlane_b32 s8, v249, 26
	v_readlane_b32 s9, v249, 27
	v_add_u32_e32 v18, 0xffffc000, v102
	v_mov_b64_e32 v[96:97], 0x1000
	v_mov_b64_e32 v[20:21], 0
	v_mov_b64_e32 v[16:17], s[8:9]

.LBB0_954:
	s_or_b64 exec, exec, s[56:57]
	v_lshlrev_b32_e32 v19, 6, v18
	v_and_b32_e32 v29, 0xfc0, v19
	v_and_b32_e32 v18, 0xffffffc0, v18
	v_mul_hi_u32_u24_e32 v35, v96, v29
	v_mul_u32_u24_e32 v34, v96, v29
	v_lshl_add_u64 v[94:95], v[34:35], 2, v[94:95]
	v_ashrrev_i32_e32 v19, 31, v18
	v_lshl_add_u64 v[94:95], v[18:19], 2, v[94:95]
	v_lshl_add_u64 v[94:95], v[94:95], 0, v[24:25]
	v_lshlrev_b64 v[22:23], 2, v[96:97]
	v_lshl_add_u64 v[34:35], v[94:95], 0, v[22:23]
	v_lshl_add_u64 v[98:99], v[34:35], 0, v[22:23]
	v_lshl_add_u64 v[38:39], v[98:99], 0, v[22:23]
	v_lshl_add_u64 v[40:41], v[38:39], 0, v[22:23]
	v_lshl_add_u64 v[42:43], v[40:41], 0, v[22:23]
	v_lshl_add_u64 v[44:45], v[42:43], 0, v[22:23]
	v_lshl_add_u64 v[46:47], v[44:45], 0, v[22:23]
	global_load_dword v96, v[94:95], off
	global_load_dword v97, v[34:35], off
	s_nop 0
	global_load_dword v34, v[98:99], off
	global_load_dword v35, v[38:39], off
	s_nop 0
	global_load_dword v98, v[40:41], off
	global_load_dword v99, v[42:43], off
	s_nop 0
	global_load_dword v40, v[44:45], off
	global_load_dword v41, v[46:47], off
	v_lshl_add_u64 v[38:39], v[46:47], 0, v[22:23]
	global_load_dword v94, v[38:39], off
	v_lshl_add_u64 v[38:39], v[38:39], 0, v[22:23]
	v_lshl_add_u64 v[42:43], v[38:39], 0, v[22:23]
	global_load_dword v95, v[38:39], off
	v_cmp_ne_u64_e64 s[34:35], 0, v[20:21]
	global_load_dword v38, v[42:43], off
	v_lshl_add_u64 v[42:43], v[42:43], 0, v[22:23]
	v_lshl_add_u64 v[44:45], v[42:43], 0, v[22:23]
	global_load_dword v39, v[42:43], off
	s_nop 0
	global_load_dword v42, v[44:45], off
	v_lshl_add_u64 v[44:45], v[44:45], 0, v[22:23]
	global_load_dword v43, v[44:45], off
	v_lshl_add_u64 v[44:45], v[44:45], 0, v[22:23]
	global_load_dword v46, v[44:45], off
	v_lshl_add_u64 v[44:45], v[44:45], 0, v[22:23]
	v_lshl_add_u64 v[48:49], v[44:45], 0, v[22:23]
	global_load_dword v47, v[44:45], off
	s_nop 0
	global_load_dword v44, v[48:49], off
	v_lshl_add_u64 v[48:49], v[48:49], 0, v[22:23]
	v_lshl_add_u64 v[50:51], v[48:49], 0, v[22:23]
	global_load_dword v45, v[48:49], off
	s_nop 0
	global_load_dword v48, v[50:51], off
	v_lshl_add_u64 v[50:51], v[50:51], 0, v[22:23]
	v_lshl_add_u64 v[52:53], v[50:51], 0, v[22:23]
	global_load_dword v49, v[50:51], off
	s_nop 0
	global_load_dword v50, v[52:53], off
	v_lshl_add_u64 v[52:53], v[52:53], 0, v[22:23]
	global_load_dword v51, v[52:53], off
	v_lshl_add_u64 v[52:53], v[52:53], 0, v[22:23]
	global_load_dword v54, v[52:53], off
	v_lshl_add_u64 v[52:53], v[52:53], 0, v[22:23]
	v_lshl_add_u64 v[56:57], v[52:53], 0, v[22:23]
	global_load_dword v55, v[52:53], off
	s_nop 0
	global_load_dword v52, v[56:57], off
	v_lshl_add_u64 v[56:57], v[56:57], 0, v[22:23]
	v_lshl_add_u64 v[58:59], v[56:57], 0, v[22:23]
	global_load_dword v53, v[56:57], off
	s_nop 0
	global_load_dword v56, v[58:59], off
	v_lshl_add_u64 v[58:59], v[58:59], 0, v[22:23]
	v_lshl_add_u64 v[60:61], v[58:59], 0, v[22:23]
	global_load_dword v57, v[58:59], off
	s_nop 0
	global_load_dword v58, v[60:61], off
	v_lshl_add_u64 v[60:61], v[60:61], 0, v[22:23]
	global_load_dword v59, v[60:61], off
	v_lshl_add_u64 v[60:61], v[60:61], 0, v[22:23]
	global_load_dword v62, v[60:61], off
	v_lshl_add_u64 v[60:61], v[60:61], 0, v[22:23]
	v_lshl_add_u64 v[64:65], v[60:61], 0, v[22:23]
	global_load_dword v63, v[60:61], off
	s_nop 0
	global_load_dword v60, v[64:65], off
	v_lshl_add_u64 v[64:65], v[64:65], 0, v[22:23]
	v_lshl_add_u64 v[66:67], v[64:65], 0, v[22:23]
	global_load_dword v61, v[64:65], off
	s_nop 0
	global_load_dword v64, v[66:67], off
	v_lshl_add_u64 v[66:67], v[66:67], 0, v[22:23]
	v_lshl_add_u64 v[68:69], v[66:67], 0, v[22:23]
	global_load_dword v65, v[66:67], off
	s_nop 0
	global_load_dword v66, v[68:69], off
	v_lshl_add_u64 v[68:69], v[68:69], 0, v[22:23]
	global_load_dword v67, v[68:69], off
	v_lshl_add_u64 v[68:69], v[68:69], 0, v[22:23]
	global_load_dword v70, v[68:69], off
	v_lshl_add_u64 v[68:69], v[68:69], 0, v[22:23]
	v_lshl_add_u64 v[72:73], v[68:69], 0, v[22:23]
	global_load_dword v71, v[68:69], off
	s_nop 0
	global_load_dword v68, v[72:73], off
	v_lshl_add_u64 v[72:73], v[72:73], 0, v[22:23]
	v_lshl_add_u64 v[74:75], v[72:73], 0, v[22:23]
	global_load_dword v69, v[72:73], off
	s_nop 0
	global_load_dword v72, v[74:75], off
	v_lshl_add_u64 v[74:75], v[74:75], 0, v[22:23]
	v_lshl_add_u64 v[76:77], v[74:75], 0, v[22:23]
	global_load_dword v73, v[74:75], off
	s_nop 0
	global_load_dword v74, v[76:77], off
	v_lshl_add_u64 v[76:77], v[76:77], 0, v[22:23]
	global_load_dword v75, v[76:77], off
	v_lshl_add_u64 v[76:77], v[76:77], 0, v[22:23]
	global_load_dword v78, v[76:77], off
	v_lshl_add_u64 v[76:77], v[76:77], 0, v[22:23]
	v_lshl_add_u64 v[80:81], v[76:77], 0, v[22:23]
	global_load_dword v79, v[76:77], off
	s_nop 0
	global_load_dword v76, v[80:81], off
	v_lshl_add_u64 v[80:81], v[80:81], 0, v[22:23]
	v_lshl_add_u64 v[82:83], v[80:81], 0, v[22:23]
	global_load_dword v77, v[80:81], off
	s_nop 0
	global_load_dword v80, v[82:83], off
	v_lshl_add_u64 v[82:83], v[82:83], 0, v[22:23]
	v_lshl_add_u64 v[84:85], v[82:83], 0, v[22:23]
	global_load_dword v81, v[82:83], off
	s_nop 0
	global_load_dword v82, v[84:85], off
	v_lshl_add_u64 v[84:85], v[84:85], 0, v[22:23]
	global_load_dword v83, v[84:85], off
	v_lshl_add_u64 v[84:85], v[84:85], 0, v[22:23]
	global_load_dword v86, v[84:85], off
	v_lshl_add_u64 v[84:85], v[84:85], 0, v[22:23]
	v_lshl_add_u64 v[88:89], v[84:85], 0, v[22:23]
	global_load_dword v87, v[84:85], off
	s_nop 0
	global_load_dword v84, v[88:89], off
	v_lshl_add_u64 v[88:89], v[88:89], 0, v[22:23]
	v_lshl_add_u64 v[90:91], v[88:89], 0, v[22:23]
	global_load_dword v85, v[88:89], off
	s_nop 0
	global_load_dword v88, v[90:91], off
	v_lshl_add_u64 v[90:91], v[90:91], 0, v[22:23]
	v_lshl_add_u64 v[92:93], v[90:91], 0, v[22:23]
	global_load_dword v89, v[90:91], off
	s_nop 0
	global_load_dword v90, v[92:93], off
	v_lshl_add_u64 v[92:93], v[92:93], 0, v[22:23]
	v_lshl_add_u64 v[36:37], v[92:93], 0, v[22:23]
	v_lshl_add_u64 v[22:23], v[36:37], 0, v[22:23]
	global_load_dword v91, v[92:93], off
	s_nop 0
	global_load_dword v92, v[36:37], off
	global_load_dword v93, v[22:23], off
	v_or_b32_e32 v18, v18, v26
	v_ashrrev_i32_e32 v19, 31, v18
	v_lshlrev_b64 v[18:19], 13, v[18:19]
	v_lshl_add_u64 v[16:17], v[16:17], 0, v[18:19]
	v_lshlrev_b32_e32 v18, 1, v29
	v_mov_b32_e32 v19, v25
	v_lshl_add_u64 v[100:101], v[16:17], 0, v[18:19]
	v_mov_b32_e32 v136, 1
	v_add_u32_e32 v102, s41, v102
	s_mov_b32 s8, 0x1b400
	s_mov_b64 s[10:11], s[72:73]
	s_and_saveexec_b64 s[56:57], s[34:35]
	s_cbranch_execz .Lcv_nogs
	v_mbcnt_lo_u32_b32 v22, -1, 0
	v_mbcnt_hi_u32_b32 v22, -1, v22
	v_add_u32_e32 v22, v22, v29
	v_lshlrev_b32_e32 v22, 2, v22
	v_mov_b32_e32 v23, v25
	v_lshl_add_u64 v[22:23], v[20:21], 0, v[22:23]
	global_load_dword v197, v[22:23], off
	v_mov_b32_e32 v136, 2
.Lcv_nogs:
	s_or_b64 exec, exec, s[56:57]
.LBB0_957:
	s_or_b64 exec, exec, s[54:55]
.LBB0_958:
	s_or_b64 exec, exec, s[52:53]
.LBB0_959:
	s_andn2_saveexec_b64 s[34:35], s[50:51]
	s_cbranch_execz .LBB0_961
	v_mov_b32_e32 v35, 0
	v_mov_b32_e32 v37, 0
	v_mov_b32_e32 v39, 0
	v_mov_b32_e32 v41, 0
	v_mov_b32_e32 v43, 0
	v_mov_b32_e32 v45, 0
	v_mov_b32_e32 v47, 0
	v_mov_b32_e32 v49, 0
	v_mov_b32_e32 v51, 0
	v_mov_b32_e32 v53, 0
	v_mov_b32_e32 v55, 0
	v_mov_b32_e32 v57, 0
	v_mov_b32_e32 v59, 0
	v_mov_b32_e32 v61, 0
	v_mov_b32_e32 v63, 0
	v_mov_b32_e32 v65, 0
	ds_read_b32 v226, v139 offset:27136
	ds_read_b32 v227, v139 offset:27392
	ds_read_b128 v[82:85], v25 offset:35456
	ds_read_b32 v29, v139 offset:27648
	ds_read_b128 v[86:89], v25 offset:35584
	ds_read_b32 v136, v139 offset:27904
	ds_read_b128 v[90:93], v25 offset:35712
	ds_read_b32 v197, v139 offset:28160
	ds_read_b128 v[94:97], v25 offset:35840
	s_waitcnt lgkmcnt(8)
	v_mul_f32_e32 v34, -1.0, v226
	ds_read_b32 v226, v139 offset:28416
	ds_read_b128 v[98:101], v25 offset:35968
	ds_read_b128 v[198:201], v25 offset:35984
	s_waitcnt lgkmcnt(9)
	v_pk_fma_f32 v[70:71], v[82:83], v[34:35], 0 op_sel_hi:[1,1,0]
	v_add_f32_e32 v70, v70, v71
	v_sub_f32_e64 v35, -v227, v70
	ds_read_b32 v227, v139 offset:28672
	ds_read_b128 v[202:205], v25 offset:36096
	ds_read_b128 v[206:209], v25 offset:36112
	s_waitcnt lgkmcnt(10)
	v_pk_fma_f32 v[66:67], v[86:87], v[34:35], 0 op_sel_hi:[1,1,0]
	v_add_f32_e32 v66, v66, v67
	v_sub_f32_e64 v36, -v29, v66
	ds_read_b32 v29, v139 offset:28928
	ds_read_b128 v[210:213], v25 offset:36224
	ds_read_b128 v[214:217], v25 offset:36240
	s_waitcnt lgkmcnt(11)
	v_pk_fma_f32 v[70:71], v[90:91], v[34:35], 0 op_sel_hi:[1,1,0]
	v_pk_fma_f32 v[72:73], v[92:93], v[36:37], 0 op_sel_hi:[1,1,0]
	v_add_f32_e32 v70, v70, v71
	v_add_f32_e32 v72, v72, v73
	v_add_f32_e32 v70, v70, v72
	v_sub_f32_e64 v37, -v136, v70
	ds_read_b32 v136, v139 offset:29184
	ds_read_b128 v[218:221], v25 offset:36352
	ds_read_b128 v[222:225], v25 offset:36368
	s_waitcnt lgkmcnt(12)
	v_pk_fma_f32 v[66:67], v[94:95], v[34:35], 0 op_sel_hi:[1,1,0]
	v_pk_fma_f32 v[68:69], v[96:97], v[36:37], 0 op_sel_hi:[1,1,0]
	v_add_f32_e32 v66, v66, v67
	v_add_f32_e32 v68, v68, v69
	v_add_f32_e32 v66, v66, v68
	v_sub_f32_e64 v38, -v197, v66
	ds_read_b32 v197, v139 offset:29440
	ds_read_b128 v[16:19], v25 offset:36480
	ds_read_b128 v[20:23], v25 offset:36496
	s_waitcnt lgkmcnt(13)
	v_pk_fma_f32 v[70:71], v[98:99], v[34:35], 0 op_sel_hi:[1,1,0]
	v_pk_fma_f32 v[72:73], v[100:101], v[36:37], 0 op_sel_hi:[1,1,0]
	ds_read_b128 v[74:77], v25 offset:36512
	s_waitcnt lgkmcnt(13)
	v_pk_fma_f32 v[70:71], v[198:199], v[38:39], v[70:71]
	v_add_f32_e32 v70, v70, v71
	v_add_f32_e32 v72, v72, v73
	v_add_f32_e32 v70, v70, v72
	v_sub_f32_e64 v39, -v226, v70
	ds_read_b32 v226, v139 offset:29696
	ds_read_b128 v[78:81], v25 offset:36608
	s_waitcnt lgkmcnt(13)
	v_pk_fma_f32 v[66:67], v[202:203], v[34:35], 0 op_sel_hi:[1,1,0]
	v_pk_fma_f32 v[68:69], v[204:205], v[36:37], 0 op_sel_hi:[1,1,0]
	ds_read_b128 v[82:85], v25 offset:36624
	ds_read_b128 v[86:89], v25 offset:36640
	s_waitcnt lgkmcnt(14)
	v_pk_fma_f32 v[66:67], v[206:207], v[38:39], v[66:67]
	v_add_f32_e32 v66, v66, v67
	v_add_f32_e32 v68, v68, v69
	v_add_f32_e32 v66, v66, v68
	v_sub_f32_e64 v40, -v227, v66
	ds_read_b32 v227, v139 offset:29952
	s_waitcnt lgkmcnt(13)
	v_pk_fma_f32 v[70:71], v[210:211], v[34:35], 0 op_sel_hi:[1,1,0]
	v_pk_fma_f32 v[72:73], v[212:213], v[36:37], 0 op_sel_hi:[1,1,0]
	ds_read_b128 v[90:93], v25 offset:36736
	ds_read_b128 v[94:97], v25 offset:36752
	s_waitcnt lgkmcnt(14)
	v_pk_fma_f32 v[70:71], v[214:215], v[38:39], v[70:71]
	v_pk_fma_f32 v[72:73], v[216:217], v[40:41], v[72:73]
	ds_read_b128 v[98:101], v25 offset:36768
	v_add_f32_e32 v70, v70, v71
	v_add_f32_e32 v72, v72, v73
	v_add_f32_e32 v70, v70, v72
	v_sub_f32_e64 v41, -v29, v70
	s_waitcnt lgkmcnt(13)
	v_pk_fma_f32 v[66:67], v[218:219], v[34:35], 0 op_sel_hi:[1,1,0]
	v_pk_fma_f32 v[68:69], v[220:221], v[36:37], 0 op_sel_hi:[1,1,0]
	ds_read_b32 v29, v139 offset:30208
	ds_read_b128 v[198:201], v25 offset:36864
	s_waitcnt lgkmcnt(14)
	v_pk_fma_f32 v[66:67], v[222:223], v[38:39], v[66:67]
	v_pk_fma_f32 v[68:69], v[224:225], v[40:41], v[68:69]
	ds_read_b128 v[202:205], v25 offset:36880
	v_add_f32_e32 v66, v66, v67
	v_add_f32_e32 v68, v68, v69
	v_add_f32_e32 v66, v66, v68
	v_sub_f32_e64 v42, -v136, v66
	s_waitcnt lgkmcnt(13)
	v_pk_fma_f32 v[70:71], v[16:17], v[34:35], 0 op_sel_hi:[1,1,0]
	v_pk_fma_f32 v[72:73], v[18:19], v[36:37], 0 op_sel_hi:[1,1,0]
	ds_read_b128 v[206:209], v25 offset:36896
	ds_read_b32 v136, v139 offset:30464
	s_waitcnt lgkmcnt(14)
	v_pk_fma_f32 v[70:71], v[20:21], v[38:39], v[70:71]
	v_pk_fma_f32 v[72:73], v[22:23], v[40:41], v[72:73]
	ds_read_b128 v[210:213], v25 offset:36992
	s_waitcnt lgkmcnt(14)
	v_pk_fma_f32 v[70:71], v[74:75], v[42:43], v[70:71]
	ds_read_b128 v[214:217], v25 offset:37008
	v_add_f32_e32 v70, v70, v71
	v_add_f32_e32 v72, v72, v73
	v_add_f32_e32 v70, v70, v72
	v_sub_f32_e64 v43, -v197, v70
	s_waitcnt lgkmcnt(13)
	v_pk_fma_f32 v[66:67], v[78:79], v[34:35], 0 op_sel_hi:[1,1,0]
	v_pk_fma_f32 v[68:69], v[80:81], v[36:37], 0 op_sel_hi:[1,1,0]
	ds_read_b128 v[218:221], v25 offset:37024
	ds_read_b128 v[222:225], v25 offset:37040
	s_waitcnt lgkmcnt(14)
	v_pk_fma_f32 v[66:67], v[82:83], v[38:39], v[66:67]
	v_pk_fma_f32 v[68:69], v[84:85], v[40:41], v[68:69]
	ds_read_b32 v197, v139 offset:30720
	s_waitcnt lgkmcnt(14)
	v_pk_fma_f32 v[66:67], v[86:87], v[42:43], v[66:67]
	ds_read_b128 v[16:19], v25 offset:37120
	v_add_f32_e32 v66, v66, v67
	v_add_f32_e32 v68, v68, v69
	v_add_f32_e32 v66, v66, v68
	v_sub_f32_e64 v44, -v226, v66
	s_waitcnt lgkmcnt(13)
	v_pk_fma_f32 v[70:71], v[90:91], v[34:35], 0 op_sel_hi:[1,1,0]
	v_pk_fma_f32 v[72:73], v[92:93], v[36:37], 0 op_sel_hi:[1,1,0]
	ds_read_b128 v[20:23], v25 offset:37136
	ds_read_b128 v[74:77], v25 offset:37152
	s_waitcnt lgkmcnt(14)
	v_pk_fma_f32 v[70:71], v[94:95], v[38:39], v[70:71]
	v_pk_fma_f32 v[72:73], v[96:97], v[40:41], v[72:73]
	ds_read_b128 v[78:81], v25 offset:37168
	s_waitcnt lgkmcnt(14)
	v_pk_fma_f32 v[70:71], v[98:99], v[42:43], v[70:71]
	v_pk_fma_f32 v[72:73], v[100:101], v[44:45], v[72:73]
	ds_read_b32 v226, v139 offset:30976
	v_add_f32_e32 v70, v70, v71
	v_add_f32_e32 v72, v72, v73
	v_add_f32_e32 v70, v70, v72
	v_sub_f32_e64 v45, -v227, v70
	s_waitcnt lgkmcnt(13)
	v_pk_fma_f32 v[66:67], v[198:199], v[34:35], 0 op_sel_hi:[1,1,0]
	v_pk_fma_f32 v[68:69], v[200:201], v[36:37], 0 op_sel_hi:[1,1,0]
	ds_read_b128 v[82:85], v25 offset:37248
	ds_read_b128 v[86:89], v25 offset:37264
	s_waitcnt lgkmcnt(14)
	v_pk_fma_f32 v[66:67], v[202:203], v[38:39], v[66:67]
	v_pk_fma_f32 v[68:69], v[204:205], v[40:41], v[68:69]
	ds_read_b128 v[90:93], v25 offset:37280
	s_waitcnt lgkmcnt(14)
	v_pk_fma_f32 v[66:67], v[206:207], v[42:43], v[66:67]
	v_pk_fma_f32 v[68:69], v[208:209], v[44:45], v[68:69]
	ds_read_b128 v[94:97], v25 offset:37296
	v_add_f32_e32 v66, v66, v67
	v_add_f32_e32 v68, v68, v69
	v_add_f32_e32 v66, v66, v68
	v_sub_f32_e64 v46, -v29, v66
	s_waitcnt lgkmcnt(13)
	v_pk_fma_f32 v[70:71], v[210:211], v[34:35], 0 op_sel_hi:[1,1,0]
	v_pk_fma_f32 v[72:73], v[212:213], v[36:37], 0 op_sel_hi:[1,1,0]
	ds_read_b32 v227, v139 offset:31232
	ds_read_b128 v[98:101], v25 offset:37376
	s_waitcnt lgkmcnt(14)
	v_pk_fma_f32 v[70:71], v[214:215], v[38:39], v[70:71]
	v_pk_fma_f32 v[72:73], v[216:217], v[40:41], v[72:73]
	ds_read_b128 v[198:201], v25 offset:37392
	s_waitcnt lgkmcnt(14)
	v_pk_fma_f32 v[70:71], v[218:219], v[42:43], v[70:71]
	v_pk_fma_f32 v[72:73], v[220:221], v[44:45], v[72:73]
	ds_read_b128 v[202:205], v25 offset:37408
	s_waitcnt lgkmcnt(14)
	v_pk_fma_f32 v[70:71], v[222:223], v[46:47], v[70:71]
	ds_read_b128 v[206:209], v25 offset:37424
	v_add_f32_e32 v70, v70, v71
	v_add_f32_e32 v72, v72, v73
	v_add_f32_e32 v70, v70, v72
	v_sub_f32_e64 v47, -v136, v70
	s_waitcnt lgkmcnt(13)
	v_pk_fma_f32 v[66:67], v[16:17], v[34:35], 0 op_sel_hi:[1,1,0]
	v_pk_fma_f32 v[68:69], v[18:19], v[36:37], 0 op_sel_hi:[1,1,0]
	ds_read_b32 v29, v139 offset:31488
	ds_read_b128 v[210:213], v25 offset:37504
	s_waitcnt lgkmcnt(14)
	v_pk_fma_f32 v[66:67], v[20:21], v[38:39], v[66:67]
	v_pk_fma_f32 v[68:69], v[22:23], v[40:41], v[68:69]
	ds_read_b128 v[214:217], v25 offset:37520
	s_waitcnt lgkmcnt(14)
	v_pk_fma_f32 v[66:67], v[74:75], v[42:43], v[66:67]
	v_pk_fma_f32 v[68:69], v[76:77], v[44:45], v[68:69]
	ds_read_b128 v[218:221], v25 offset:37536
	s_waitcnt lgkmcnt(14)
	v_pk_fma_f32 v[66:67], v[78:79], v[46:47], v[66:67]
	ds_read_b128 v[222:225], v25 offset:37552
	v_add_f32_e32 v66, v66, v67
	v_add_f32_e32 v68, v68, v69
	v_add_f32_e32 v66, v66, v68
	v_sub_f32_e64 v48, -v197, v66
	s_waitcnt lgkmcnt(13)
	v_pk_fma_f32 v[70:71], v[82:83], v[34:35], 0 op_sel_hi:[1,1,0]
	v_pk_fma_f32 v[72:73], v[84:85], v[36:37], 0 op_sel_hi:[1,1,0]
	ds_read_b128 v[16:19], v25 offset:37568
	ds_read_b32 v136, v139 offset:31744
	s_waitcnt lgkmcnt(14)
	v_pk_fma_f32 v[70:71], v[86:87], v[38:39], v[70:71]
	v_pk_fma_f32 v[72:73], v[88:89], v[40:41], v[72:73]
	ds_read_b128 v[20:23], v25 offset:37632
	s_waitcnt lgkmcnt(14)
	v_pk_fma_f32 v[70:71], v[90:91], v[42:43], v[70:71]
	v_pk_fma_f32 v[72:73], v[92:93], v[44:45], v[72:73]
	ds_read_b128 v[74:77], v25 offset:37648
	s_waitcnt lgkmcnt(14)
	v_pk_fma_f32 v[70:71], v[94:95], v[46:47], v[70:71]
	v_pk_fma_f32 v[72:73], v[96:97], v[48:49], v[72:73]
	ds_read_b128 v[78:81], v25 offset:37664
	v_add_f32_e32 v70, v70, v71
	v_add_f32_e32 v72, v72, v73
	v_add_f32_e32 v70, v70, v72
	v_sub_f32_e64 v49, -v226, v70
	s_waitcnt lgkmcnt(13)
	v_pk_fma_f32 v[66:67], v[98:99], v[34:35], 0 op_sel_hi:[1,1,0]
	v_pk_fma_f32 v[68:69], v[100:101], v[36:37], 0 op_sel_hi:[1,1,0]
	ds_read_b128 v[82:85], v25 offset:37680
	ds_read_b128 v[86:89], v25 offset:37696
	s_waitcnt lgkmcnt(14)
	v_pk_fma_f32 v[66:67], v[198:199], v[38:39], v[66:67]
	v_pk_fma_f32 v[68:69], v[200:201], v[40:41], v[68:69]
	ds_read_b32 v197, v139 offset:32000
	s_waitcnt lgkmcnt(14)
	v_pk_fma_f32 v[66:67], v[202:203], v[42:43], v[66:67]
	v_pk_fma_f32 v[68:69], v[204:205], v[44:45], v[68:69]
	ds_read_b128 v[90:93], v25 offset:37760
	s_waitcnt lgkmcnt(14)
	v_pk_fma_f32 v[66:67], v[206:207], v[46:47], v[66:67]
	v_pk_fma_f32 v[68:69], v[208:209], v[48:49], v[68:69]
	ds_read_b128 v[94:97], v25 offset:37776
	v_add_f32_e32 v66, v66, v67
	v_add_f32_e32 v68, v68, v69
	v_add_f32_e32 v66, v66, v68
	v_sub_f32_e64 v50, -v227, v66
	s_waitcnt lgkmcnt(13)
	v_pk_fma_f32 v[70:71], v[210:211], v[34:35], 0 op_sel_hi:[1,1,0]
	v_pk_fma_f32 v[72:73], v[212:213], v[36:37], 0 op_sel_hi:[1,1,0]
	ds_read_b128 v[98:101], v25 offset:37792
	ds_read_b128 v[198:201], v25 offset:37808
	s_waitcnt lgkmcnt(14)
	v_pk_fma_f32 v[70:71], v[214:215], v[38:39], v[70:71]
	v_pk_fma_f32 v[72:73], v[216:217], v[40:41], v[72:73]
	ds_read_b128 v[202:205], v25 offset:37824
	s_waitcnt lgkmcnt(14)
	v_pk_fma_f32 v[70:71], v[218:219], v[42:43], v[70:71]
	v_pk_fma_f32 v[72:73], v[220:221], v[44:45], v[72:73]
	ds_read_b32 v226, v139 offset:32256
	s_waitcnt lgkmcnt(14)
	v_pk_fma_f32 v[70:71], v[222:223], v[46:47], v[70:71]
	v_pk_fma_f32 v[72:73], v[224:225], v[48:49], v[72:73]
	ds_read_b128 v[206:209], v25 offset:37888
	s_waitcnt lgkmcnt(14)
	v_pk_fma_f32 v[70:71], v[16:17], v[50:51], v[70:71]
	ds_read_b128 v[210:213], v25 offset:37904
	v_add_f32_e32 v70, v70, v71
	v_add_f32_e32 v72, v72, v73
	v_add_f32_e32 v70, v70, v72
	v_sub_f32_e64 v51, -v29, v70
	s_waitcnt lgkmcnt(13)
	v_pk_fma_f32 v[66:67], v[20:21], v[34:35], 0 op_sel_hi:[1,1,0]
	v_pk_fma_f32 v[68:69], v[22:23], v[36:37], 0 op_sel_hi:[1,1,0]
	ds_read_b128 v[214:217], v25 offset:37920
	ds_read_b128 v[218:221], v25 offset:37936
	s_waitcnt lgkmcnt(14)
	v_pk_fma_f32 v[66:67], v[74:75], v[38:39], v[66:67]
	v_pk_fma_f32 v[68:69], v[76:77], v[40:41], v[68:69]
	ds_read_b128 v[222:225], v25 offset:37952
	s_waitcnt lgkmcnt(14)
	v_pk_fma_f32 v[66:67], v[78:79], v[42:43], v[66:67]
	v_pk_fma_f32 v[68:69], v[80:81], v[44:45], v[68:69]
	ds_read_b32 v227, v139 offset:32512
	s_waitcnt lgkmcnt(14)
	v_pk_fma_f32 v[66:67], v[82:83], v[46:47], v[66:67]
	v_pk_fma_f32 v[68:69], v[84:85], v[48:49], v[68:69]
	ds_read_b128 v[16:19], v25 offset:38016
	s_waitcnt lgkmcnt(14)
	v_pk_fma_f32 v[66:67], v[86:87], v[50:51], v[66:67]
	ds_read_b128 v[20:23], v25 offset:38032
	v_add_f32_e32 v66, v66, v67
	v_add_f32_e32 v68, v68, v69
	v_add_f32_e32 v66, v66, v68
	v_sub_f32_e64 v52, -v136, v66
	s_waitcnt lgkmcnt(13)
	v_pk_fma_f32 v[70:71], v[90:91], v[34:35], 0 op_sel_hi:[1,1,0]
	v_pk_fma_f32 v[72:73], v[92:93], v[36:37], 0 op_sel_hi:[1,1,0]
	ds_read_b128 v[74:77], v25 offset:38048
	ds_read_b128 v[78:81], v25 offset:38064
	s_waitcnt lgkmcnt(14)
	v_pk_fma_f32 v[70:71], v[94:95], v[38:39], v[70:71]
	v_pk_fma_f32 v[72:73], v[96:97], v[40:41], v[72:73]
	ds_read_b128 v[82:85], v25 offset:38080
	s_waitcnt lgkmcnt(14)
	v_pk_fma_f32 v[70:71], v[98:99], v[42:43], v[70:71]
	v_pk_fma_f32 v[72:73], v[100:101], v[44:45], v[72:73]
	ds_read_b128 v[86:89], v25 offset:38096
	s_waitcnt lgkmcnt(14)
	v_pk_fma_f32 v[70:71], v[198:199], v[46:47], v[70:71]
	v_pk_fma_f32 v[72:73], v[200:201], v[48:49], v[72:73]
	ds_read_b32 v29, v139 offset:32768
	s_waitcnt lgkmcnt(14)
	v_pk_fma_f32 v[70:71], v[202:203], v[50:51], v[70:71]
	v_pk_fma_f32 v[72:73], v[204:205], v[52:53], v[72:73]
	ds_read_b128 v[90:93], v25 offset:38144
	v_add_f32_e32 v70, v70, v71
	v_add_f32_e32 v72, v72, v73
	v_add_f32_e32 v70, v70, v72
	v_sub_f32_e64 v53, -v197, v70
	s_waitcnt lgkmcnt(13)
	v_pk_fma_f32 v[66:67], v[206:207], v[34:35], 0 op_sel_hi:[1,1,0]
	v_pk_fma_f32 v[68:69], v[208:209], v[36:37], 0 op_sel_hi:[1,1,0]
	ds_read_b128 v[94:97], v25 offset:38160
	ds_read_b128 v[98:101], v25 offset:38176
	s_waitcnt lgkmcnt(14)
	v_pk_fma_f32 v[66:67], v[210:211], v[38:39], v[66:67]
	v_pk_fma_f32 v[68:69], v[212:213], v[40:41], v[68:69]
	ds_read_b128 v[198:201], v25 offset:38192
	s_waitcnt lgkmcnt(14)
	v_pk_fma_f32 v[66:67], v[214:215], v[42:43], v[66:67]
	v_pk_fma_f32 v[68:69], v[216:217], v[44:45], v[68:69]
	ds_read_b128 v[202:205], v25 offset:38208
	s_waitcnt lgkmcnt(14)
	v_pk_fma_f32 v[66:67], v[218:219], v[46:47], v[66:67]
	v_pk_fma_f32 v[68:69], v[220:221], v[48:49], v[68:69]
	ds_read_b128 v[206:209], v25 offset:38224
	s_waitcnt lgkmcnt(14)
	v_pk_fma_f32 v[66:67], v[222:223], v[50:51], v[66:67]
	v_pk_fma_f32 v[68:69], v[224:225], v[52:53], v[68:69]
	ds_read_b32 v136, v139 offset:33024
	v_add_f32_e32 v66, v66, v67
	v_add_f32_e32 v68, v68, v69
	v_add_f32_e32 v66, v66, v68
	v_sub_f32_e64 v54, -v226, v66
	s_waitcnt lgkmcnt(13)
	v_pk_fma_f32 v[70:71], v[16:17], v[34:35], 0 op_sel_hi:[1,1,0]
	v_pk_fma_f32 v[72:73], v[18:19], v[36:37], 0 op_sel_hi:[1,1,0]
	ds_read_b128 v[210:213], v25 offset:38272
	ds_read_b128 v[214:217], v25 offset:38288
	s_waitcnt lgkmcnt(14)
	v_pk_fma_f32 v[70:71], v[20:21], v[38:39], v[70:71]
	v_pk_fma_f32 v[72:73], v[22:23], v[40:41], v[72:73]
	ds_read_b128 v[218:221], v25 offset:38304
	s_waitcnt lgkmcnt(14)
	v_pk_fma_f32 v[70:71], v[74:75], v[42:43], v[70:71]
	v_pk_fma_f32 v[72:73], v[76:77], v[44:45], v[72:73]
	ds_read_b128 v[222:225], v25 offset:38320
	s_waitcnt lgkmcnt(14)
	v_pk_fma_f32 v[70:71], v[78:79], v[46:47], v[70:71]
	v_pk_fma_f32 v[72:73], v[80:81], v[48:49], v[72:73]
	ds_read_b128 v[16:19], v25 offset:38336
	s_waitcnt lgkmcnt(14)
	v_pk_fma_f32 v[70:71], v[82:83], v[50:51], v[70:71]
	v_pk_fma_f32 v[72:73], v[84:85], v[52:53], v[72:73]
	ds_read_b128 v[20:23], v25 offset:38352
	s_waitcnt lgkmcnt(14)
	v_pk_fma_f32 v[70:71], v[86:87], v[54:55], v[70:71]
	ds_read_b32 v197, v139 offset:33280
	v_add_f32_e32 v70, v70, v71
	v_add_f32_e32 v72, v72, v73
	v_add_f32_e32 v70, v70, v72
	v_sub_f32_e64 v55, -v227, v70
	s_waitcnt lgkmcnt(13)
	v_pk_fma_f32 v[66:67], v[90:91], v[34:35], 0 op_sel_hi:[1,1,0]
	v_pk_fma_f32 v[68:69], v[92:93], v[36:37], 0 op_sel_hi:[1,1,0]
	ds_read_b128 v[74:77], v25 offset:38400
	ds_read_b128 v[78:81], v25 offset:38416
	s_waitcnt lgkmcnt(14)
	v_pk_fma_f32 v[66:67], v[94:95], v[38:39], v[66:67]
	v_pk_fma_f32 v[68:69], v[96:97], v[40:41], v[68:69]
	ds_read_b128 v[82:85], v25 offset:38432
	s_waitcnt lgkmcnt(14)
	v_pk_fma_f32 v[66:67], v[98:99], v[42:43], v[66:67]
	v_pk_fma_f32 v[68:69], v[100:101], v[44:45], v[68:69]
	ds_read_b128 v[86:89], v25 offset:38448
	s_waitcnt lgkmcnt(14)
	v_pk_fma_f32 v[66:67], v[198:199], v[46:47], v[66:67]
	v_pk_fma_f32 v[68:69], v[200:201], v[48:49], v[68:69]
	ds_read_b128 v[90:93], v25 offset:38464
	s_waitcnt lgkmcnt(14)
	v_pk_fma_f32 v[66:67], v[202:203], v[50:51], v[66:67]
	v_pk_fma_f32 v[68:69], v[204:205], v[52:53], v[68:69]
	ds_read_b128 v[94:97], v25 offset:38480
	s_waitcnt lgkmcnt(14)
	v_pk_fma_f32 v[66:67], v[206:207], v[54:55], v[66:67]
	ds_read_b32 v226, v139 offset:33536
	v_add_f32_e32 v66, v66, v67
	v_add_f32_e32 v68, v68, v69
	v_add_f32_e32 v66, v66, v68
	v_sub_f32_e64 v56, -v29, v66
	s_waitcnt lgkmcnt(13)
	v_pk_fma_f32 v[70:71], v[210:211], v[34:35], 0 op_sel_hi:[1,1,0]
	v_pk_fma_f32 v[72:73], v[212:213], v[36:37], 0 op_sel_hi:[1,1,0]
	ds_read_b128 v[98:101], v25 offset:38528
	ds_read_b128 v[198:201], v25 offset:38544
	s_waitcnt lgkmcnt(14)
	v_pk_fma_f32 v[70:71], v[214:215], v[38:39], v[70:71]
	v_pk_fma_f32 v[72:73], v[216:217], v[40:41], v[72:73]
	ds_read_b128 v[202:205], v25 offset:38560
	s_waitcnt lgkmcnt(14)
	v_pk_fma_f32 v[70:71], v[218:219], v[42:43], v[70:71]
	v_pk_fma_f32 v[72:73], v[220:221], v[44:45], v[72:73]
	ds_read_b128 v[206:209], v25 offset:38576
	s_waitcnt lgkmcnt(14)
	v_pk_fma_f32 v[70:71], v[222:223], v[46:47], v[70:71]
	v_pk_fma_f32 v[72:73], v[224:225], v[48:49], v[72:73]
	ds_read_b128 v[210:213], v25 offset:38592
	s_waitcnt lgkmcnt(14)
	v_pk_fma_f32 v[70:71], v[16:17], v[50:51], v[70:71]
	v_pk_fma_f32 v[72:73], v[18:19], v[52:53], v[72:73]
	ds_read_b128 v[214:217], v25 offset:38608
	s_waitcnt lgkmcnt(14)
	v_pk_fma_f32 v[70:71], v[20:21], v[54:55], v[70:71]
	v_pk_fma_f32 v[72:73], v[22:23], v[56:57], v[72:73]
	ds_read_b128 v[218:221], v25 offset:38624
	v_add_f32_e32 v70, v70, v71
	v_add_f32_e32 v72, v72, v73
	v_add_f32_e32 v70, v70, v72
	v_sub_f32_e64 v57, -v136, v70
	s_waitcnt lgkmcnt(13)
	v_pk_fma_f32 v[66:67], v[74:75], v[34:35], 0 op_sel_hi:[1,1,0]
	v_pk_fma_f32 v[68:69], v[76:77], v[36:37], 0 op_sel_hi:[1,1,0]
	ds_read_b32 v227, v139 offset:33792
	ds_read_b128 v[222:225], v25 offset:38656
	s_waitcnt lgkmcnt(14)
	v_pk_fma_f32 v[66:67], v[78:79], v[38:39], v[66:67]
	v_pk_fma_f32 v[68:69], v[80:81], v[40:41], v[68:69]
	ds_read_b128 v[16:19], v25 offset:38672
	s_waitcnt lgkmcnt(14)
	v_pk_fma_f32 v[66:67], v[82:83], v[42:43], v[66:67]
	v_pk_fma_f32 v[68:69], v[84:85], v[44:45], v[68:69]
	ds_read_b128 v[20:23], v25 offset:38688
	s_waitcnt lgkmcnt(14)
	v_pk_fma_f32 v[66:67], v[86:87], v[46:47], v[66:67]
	v_pk_fma_f32 v[68:69], v[88:89], v[48:49], v[68:69]
	ds_read_b128 v[74:77], v25 offset:38704
	s_waitcnt lgkmcnt(14)
	v_pk_fma_f32 v[66:67], v[90:91], v[50:51], v[66:67]
	v_pk_fma_f32 v[68:69], v[92:93], v[52:53], v[68:69]
	ds_read_b128 v[78:81], v25 offset:38720
	s_waitcnt lgkmcnt(14)
	v_pk_fma_f32 v[66:67], v[94:95], v[54:55], v[66:67]
	v_pk_fma_f32 v[68:69], v[96:97], v[56:57], v[68:69]
	ds_read_b128 v[82:85], v25 offset:38736
	v_add_f32_e32 v66, v66, v67
	v_add_f32_e32 v68, v68, v69
	v_add_f32_e32 v66, v66, v68
	v_sub_f32_e64 v58, -v197, v66
	s_waitcnt lgkmcnt(13)
	v_pk_fma_f32 v[70:71], v[98:99], v[34:35], 0 op_sel_hi:[1,1,0]
	v_pk_fma_f32 v[72:73], v[100:101], v[36:37], 0 op_sel_hi:[1,1,0]
	ds_read_b128 v[86:89], v25 offset:38752
	ds_read_b32 v29, v139 offset:34048
	s_waitcnt lgkmcnt(14)
	v_pk_fma_f32 v[70:71], v[198:199], v[38:39], v[70:71]
	v_pk_fma_f32 v[72:73], v[200:201], v[40:41], v[72:73]
	ds_read_b128 v[90:93], v25 offset:38784
	s_waitcnt lgkmcnt(14)
	v_pk_fma_f32 v[70:71], v[202:203], v[42:43], v[70:71]
	v_pk_fma_f32 v[72:73], v[204:205], v[44:45], v[72:73]
	ds_read_b128 v[94:97], v25 offset:38800
	s_waitcnt lgkmcnt(14)
	v_pk_fma_f32 v[70:71], v[206:207], v[46:47], v[70:71]
	v_pk_fma_f32 v[72:73], v[208:209], v[48:49], v[72:73]
	ds_read_b128 v[98:101], v25 offset:38816
	s_waitcnt lgkmcnt(14)
	v_pk_fma_f32 v[70:71], v[210:211], v[50:51], v[70:71]
	v_pk_fma_f32 v[72:73], v[212:213], v[52:53], v[72:73]
	ds_read_b128 v[198:201], v25 offset:38832
	s_waitcnt lgkmcnt(14)
	v_pk_fma_f32 v[70:71], v[214:215], v[54:55], v[70:71]
	v_pk_fma_f32 v[72:73], v[216:217], v[56:57], v[72:73]
	ds_read_b128 v[202:205], v25 offset:38848
	s_waitcnt lgkmcnt(14)
	v_pk_fma_f32 v[70:71], v[218:219], v[58:59], v[70:71]
	ds_read_b128 v[206:209], v25 offset:38864
	v_add_f32_e32 v70, v70, v71
	v_add_f32_e32 v72, v72, v73
	v_add_f32_e32 v70, v70, v72
	v_sub_f32_e64 v59, -v226, v70
	s_waitcnt lgkmcnt(13)
	v_pk_fma_f32 v[66:67], v[222:223], v[34:35], 0 op_sel_hi:[1,1,0]
	v_pk_fma_f32 v[68:69], v[224:225], v[36:37], 0 op_sel_hi:[1,1,0]
	ds_read_b128 v[210:213], v25 offset:38880
	ds_read_b32 v136, v139 offset:34304
	s_waitcnt lgkmcnt(14)
	v_pk_fma_f32 v[66:67], v[16:17], v[38:39], v[66:67]
	v_pk_fma_f32 v[68:69], v[18:19], v[40:41], v[68:69]
	ds_read_b128 v[214:217], v25 offset:38912
	s_waitcnt lgkmcnt(14)
	v_pk_fma_f32 v[66:67], v[20:21], v[42:43], v[66:67]
	v_pk_fma_f32 v[68:69], v[22:23], v[44:45], v[68:69]
	ds_read_b128 v[218:221], v25 offset:38928
	s_waitcnt lgkmcnt(14)
	v_pk_fma_f32 v[66:67], v[74:75], v[46:47], v[66:67]
	v_pk_fma_f32 v[68:69], v[76:77], v[48:49], v[68:69]
	ds_read_b128 v[222:225], v25 offset:38944
	s_waitcnt lgkmcnt(14)
	v_pk_fma_f32 v[66:67], v[78:79], v[50:51], v[66:67]
	v_pk_fma_f32 v[68:69], v[80:81], v[52:53], v[68:69]
	ds_read_b128 v[16:19], v25 offset:38960
	s_waitcnt lgkmcnt(14)
	v_pk_fma_f32 v[66:67], v[82:83], v[54:55], v[66:67]
	v_pk_fma_f32 v[68:69], v[84:85], v[56:57], v[68:69]
	ds_read_b128 v[20:23], v25 offset:38976
	s_waitcnt lgkmcnt(14)
	v_pk_fma_f32 v[66:67], v[86:87], v[58:59], v[66:67]
	ds_read_b128 v[74:77], v25 offset:38992
	v_add_f32_e32 v66, v66, v67
	v_add_f32_e32 v68, v68, v69
	v_add_f32_e32 v66, v66, v68
	v_sub_f32_e64 v60, -v227, v66
	s_waitcnt lgkmcnt(13)
	v_pk_fma_f32 v[70:71], v[90:91], v[34:35], 0 op_sel_hi:[1,1,0]
	v_pk_fma_f32 v[72:73], v[92:93], v[36:37], 0 op_sel_hi:[1,1,0]
	ds_read_b128 v[78:81], v25 offset:39008
	ds_read_b32 v197, v139 offset:34560
	s_waitcnt lgkmcnt(14)
	v_pk_fma_f32 v[70:71], v[94:95], v[38:39], v[70:71]
	v_pk_fma_f32 v[72:73], v[96:97], v[40:41], v[72:73]
	ds_read_b128 v[82:85], v25 offset:39040
	s_waitcnt lgkmcnt(14)
	v_pk_fma_f32 v[70:71], v[98:99], v[42:43], v[70:71]
	v_pk_fma_f32 v[72:73], v[100:101], v[44:45], v[72:73]
	ds_read_b128 v[86:89], v25 offset:39056
	s_waitcnt lgkmcnt(14)
	v_pk_fma_f32 v[70:71], v[198:199], v[46:47], v[70:71]
	v_pk_fma_f32 v[72:73], v[200:201], v[48:49], v[72:73]
	ds_read_b128 v[90:93], v25 offset:39072
	s_waitcnt lgkmcnt(14)
	v_pk_fma_f32 v[70:71], v[202:203], v[50:51], v[70:71]
	v_pk_fma_f32 v[72:73], v[204:205], v[52:53], v[72:73]
	ds_read_b128 v[94:97], v25 offset:39088
	s_waitcnt lgkmcnt(14)
	v_pk_fma_f32 v[70:71], v[206:207], v[54:55], v[70:71]
	v_pk_fma_f32 v[72:73], v[208:209], v[56:57], v[72:73]
	ds_read_b128 v[98:101], v25 offset:39104
	s_waitcnt lgkmcnt(14)
	v_pk_fma_f32 v[70:71], v[210:211], v[58:59], v[70:71]
	v_pk_fma_f32 v[72:73], v[212:213], v[60:61], v[72:73]
	ds_read_b128 v[198:201], v25 offset:39120
	v_add_f32_e32 v70, v70, v71
	v_add_f32_e32 v72, v72, v73
	v_add_f32_e32 v70, v70, v72
	v_sub_f32_e64 v61, -v29, v70
	s_waitcnt lgkmcnt(13)
	v_pk_fma_f32 v[66:67], v[214:215], v[34:35], 0 op_sel_hi:[1,1,0]
	v_pk_fma_f32 v[68:69], v[216:217], v[36:37], 0 op_sel_hi:[1,1,0]
	ds_read_b128 v[202:205], v25 offset:39136
	ds_read_b128 v[206:209], v25 offset:39152
	s_waitcnt lgkmcnt(14)
	v_pk_fma_f32 v[66:67], v[218:219], v[38:39], v[66:67]
	v_pk_fma_f32 v[68:69], v[220:221], v[40:41], v[68:69]
	ds_read_b32 v226, v139 offset:34816
	s_waitcnt lgkmcnt(14)
	v_pk_fma_f32 v[66:67], v[222:223], v[42:43], v[66:67]
	v_pk_fma_f32 v[68:69], v[224:225], v[44:45], v[68:69]
	ds_read_b128 v[210:213], v25 offset:39168
	s_waitcnt lgkmcnt(14)
	v_pk_fma_f32 v[66:67], v[16:17], v[46:47], v[66:67]
	v_pk_fma_f32 v[68:69], v[18:19], v[48:49], v[68:69]
	ds_read_b128 v[214:217], v25 offset:39184
	s_waitcnt lgkmcnt(14)
	v_pk_fma_f32 v[66:67], v[20:21], v[50:51], v[66:67]
	v_pk_fma_f32 v[68:69], v[22:23], v[52:53], v[68:69]
	ds_read_b128 v[218:221], v25 offset:39200
	s_waitcnt lgkmcnt(14)
	v_pk_fma_f32 v[66:67], v[74:75], v[54:55], v[66:67]
	v_pk_fma_f32 v[68:69], v[76:77], v[56:57], v[68:69]
	ds_read_b128 v[222:225], v25 offset:39216
	s_waitcnt lgkmcnt(14)
	v_pk_fma_f32 v[66:67], v[78:79], v[58:59], v[66:67]
	v_pk_fma_f32 v[68:69], v[80:81], v[60:61], v[68:69]
	ds_read_b128 v[16:19], v25 offset:39232
	v_add_f32_e32 v66, v66, v67
	v_add_f32_e32 v68, v68, v69
	v_add_f32_e32 v66, v66, v68
	v_sub_f32_e64 v62, -v136, v66
	s_waitcnt lgkmcnt(13)
	v_pk_fma_f32 v[70:71], v[82:83], v[34:35], 0 op_sel_hi:[1,1,0]
	v_pk_fma_f32 v[72:73], v[84:85], v[36:37], 0 op_sel_hi:[1,1,0]
	ds_read_b128 v[20:23], v25 offset:39248
	ds_read_b128 v[74:77], v25 offset:39264
	s_waitcnt lgkmcnt(14)
	v_pk_fma_f32 v[70:71], v[86:87], v[38:39], v[70:71]
	v_pk_fma_f32 v[72:73], v[88:89], v[40:41], v[72:73]
	ds_read_b128 v[78:81], v25 offset:39280
	s_waitcnt lgkmcnt(14)
	v_pk_fma_f32 v[70:71], v[90:91], v[42:43], v[70:71]
	v_pk_fma_f32 v[72:73], v[92:93], v[44:45], v[72:73]
	ds_read_b32 v227, v139 offset:35072
	s_waitcnt lgkmcnt(14)
	v_pk_fma_f32 v[70:71], v[94:95], v[46:47], v[70:71]
	v_pk_fma_f32 v[72:73], v[96:97], v[48:49], v[72:73]
	ds_read_b128 v[82:85], v25 offset:39296
	s_waitcnt lgkmcnt(14)
	v_pk_fma_f32 v[70:71], v[98:99], v[50:51], v[70:71]
	v_pk_fma_f32 v[72:73], v[100:101], v[52:53], v[72:73]
	ds_read_b128 v[86:89], v25 offset:39312
	s_waitcnt lgkmcnt(14)
	v_pk_fma_f32 v[70:71], v[198:199], v[54:55], v[70:71]
	v_pk_fma_f32 v[72:73], v[200:201], v[56:57], v[72:73]
	ds_read_b128 v[90:93], v25 offset:39328
	s_waitcnt lgkmcnt(14)
	v_pk_fma_f32 v[70:71], v[202:203], v[58:59], v[70:71]
	v_pk_fma_f32 v[72:73], v[204:205], v[60:61], v[72:73]
	ds_read_b128 v[94:97], v25 offset:39344
	s_waitcnt lgkmcnt(14)
	v_pk_fma_f32 v[70:71], v[206:207], v[62:63], v[70:71]
	ds_read_b128 v[98:101], v25 offset:39360
	v_add_f32_e32 v70, v70, v71
	v_add_f32_e32 v72, v72, v73
	v_add_f32_e32 v70, v70, v72
	v_sub_f32_e64 v63, -v197, v70
	s_waitcnt lgkmcnt(13)
	v_pk_fma_f32 v[66:67], v[210:211], v[34:35], 0 op_sel_hi:[1,1,0]
	v_pk_fma_f32 v[68:69], v[212:213], v[36:37], 0 op_sel_hi:[1,1,0]
	ds_read_b128 v[198:201], v25 offset:39376
	ds_read_b128 v[202:205], v25 offset:39392
	s_waitcnt lgkmcnt(14)
	v_pk_fma_f32 v[66:67], v[214:215], v[38:39], v[66:67]
	v_pk_fma_f32 v[68:69], v[216:217], v[40:41], v[68:69]
	ds_read_b128 v[206:209], v25 offset:39408
	s_waitcnt lgkmcnt(14)
	v_pk_fma_f32 v[66:67], v[218:219], v[42:43], v[66:67]
	v_pk_fma_f32 v[68:69], v[220:221], v[44:45], v[68:69]
	s_waitcnt lgkmcnt(13)
	v_pk_fma_f32 v[66:67], v[222:223], v[46:47], v[66:67]
	v_pk_fma_f32 v[68:69], v[224:225], v[48:49], v[68:69]
	s_waitcnt lgkmcnt(12)
	v_pk_fma_f32 v[66:67], v[16:17], v[50:51], v[66:67]
	v_pk_fma_f32 v[68:69], v[18:19], v[52:53], v[68:69]
	s_waitcnt lgkmcnt(11)
	v_pk_fma_f32 v[66:67], v[20:21], v[54:55], v[66:67]
	v_pk_fma_f32 v[68:69], v[22:23], v[56:57], v[68:69]
	s_waitcnt lgkmcnt(10)
	v_pk_fma_f32 v[66:67], v[74:75], v[58:59], v[66:67]
	v_pk_fma_f32 v[68:69], v[76:77], v[60:61], v[68:69]
	s_waitcnt lgkmcnt(9)
	v_pk_fma_f32 v[66:67], v[78:79], v[62:63], v[66:67]
	v_add_f32_e32 v66, v66, v67
	v_add_f32_e32 v68, v68, v69
	v_add_f32_e32 v66, v66, v68
	v_sub_f32_e64 v64, -v226, v66
	s_waitcnt lgkmcnt(7)
	v_pk_fma_f32 v[70:71], v[82:83], v[34:35], 0 op_sel_hi:[1,1,0]
	v_pk_fma_f32 v[72:73], v[84:85], v[36:37], 0 op_sel_hi:[1,1,0]
	s_waitcnt lgkmcnt(6)
	v_pk_fma_f32 v[70:71], v[86:87], v[38:39], v[70:71]
	v_pk_fma_f32 v[72:73], v[88:89], v[40:41], v[72:73]
	s_waitcnt lgkmcnt(5)
	v_pk_fma_f32 v[70:71], v[90:91], v[42:43], v[70:71]
	v_pk_fma_f32 v[72:73], v[92:93], v[44:45], v[72:73]
	s_waitcnt lgkmcnt(4)
	v_pk_fma_f32 v[70:71], v[94:95], v[46:47], v[70:71]
	v_pk_fma_f32 v[72:73], v[96:97], v[48:49], v[72:73]
	s_waitcnt lgkmcnt(3)
	v_pk_fma_f32 v[70:71], v[98:99], v[50:51], v[70:71]
	v_pk_fma_f32 v[72:73], v[100:101], v[52:53], v[72:73]
	s_waitcnt lgkmcnt(2)
	v_pk_fma_f32 v[70:71], v[198:199], v[54:55], v[70:71]
	v_pk_fma_f32 v[72:73], v[200:201], v[56:57], v[72:73]
	s_waitcnt lgkmcnt(1)
	v_pk_fma_f32 v[70:71], v[202:203], v[58:59], v[70:71]
	v_pk_fma_f32 v[72:73], v[204:205], v[60:61], v[72:73]
	s_waitcnt lgkmcnt(0)
	v_pk_fma_f32 v[70:71], v[206:207], v[62:63], v[70:71]
	v_pk_fma_f32 v[72:73], v[208:209], v[64:65], v[72:73]
	v_add_f32_e32 v70, v70, v71
	v_add_f32_e32 v72, v72, v73
	v_add_f32_e32 v70, v70, v72
	v_sub_f32_e64 v65, -v227, v70
	v_add_u32_e32 v29, 0x13c00, v127
	v_cvt_pk_bf16_f32 v16, v34, v35
	v_cvt_pk_bf16_f32 v17, v36, v37
	v_cvt_pk_bf16_f32 v18, v38, v39
	v_cvt_pk_bf16_f32 v19, v40, v41
	ds_write_b128 v29, v[16:19]
	v_cvt_pk_bf16_f32 v20, v42, v43
	v_cvt_pk_bf16_f32 v21, v44, v45
	v_cvt_pk_bf16_f32 v22, v46, v47
	v_cvt_pk_bf16_f32 v23, v48, v49
	ds_write_b128 v29, v[20:23] offset:16
	v_cvt_pk_bf16_f32 v16, v50, v51
	v_cvt_pk_bf16_f32 v17, v52, v53
	v_cvt_pk_bf16_f32 v18, v54, v55
	v_cvt_pk_bf16_f32 v19, v56, v57
	ds_write_b128 v29, v[16:19] offset:32
	v_cvt_pk_bf16_f32 v20, v58, v59
	v_cvt_pk_bf16_f32 v21, v60, v61
	v_cvt_pk_bf16_f32 v22, v62, v63
	v_cvt_pk_bf16_f32 v23, v64, v65
	ds_write_b128 v29, v[20:23] offset:48

.LBB0_1729:
	s_cmp_ge_i32 s36, s33
	s_cbranch_scc1 .LBB0_1760
	s_movk_i32 s0, 0xd00
	v_cmp_gt_i32_e64 s[2:3], s0, v52
	s_mov_b32 s0, 0x4ec4ec4f
	v_mul_hi_i32 v54, v52, s0
	v_lshrrev_b32_e32 v55, 31, v54
	v_ashrrev_i32_e32 v54, 3, v54
	v_add_u32_e32 v54, v54, v55
	v_and_b32_e32 v84, 0xf0, v53
	v_add_u32_e32 v53, 0x200, v52
	v_mul_lo_u32 v55, v54, 26
	s_movk_i32 s1, 0x1b0
	v_sub_u32_e32 v55, v52, v55
	v_mul_lo_u32 v66, v54, s1
	v_mul_hi_i32 v54, v53, s0
	v_lshlrev_b32_e32 v67, 4, v55
	v_lshrrev_b32_e32 v55, 31, v54
	v_ashrrev_i32_e32 v54, 3, v54
	v_add_u32_e32 v54, v54, v55
	v_add_u32_e32 v58, 0x400, v52
	v_mul_lo_u32 v55, v54, 26
	v_sub_u32_e32 v55, v53, v55
	v_mul_lo_u32 v68, v54, s1
	v_mul_hi_i32 v54, v58, s0
	v_lshlrev_b32_e32 v69, 4, v55
	v_lshrrev_b32_e32 v55, 31, v54
	v_ashrrev_i32_e32 v54, 3, v54
	v_add_u32_e32 v54, v54, v55
	v_add_u32_e32 v60, 0x600, v52
	v_mul_lo_u32 v55, v54, 26
	v_sub_u32_e32 v55, v58, v55
	v_mul_lo_u32 v70, v54, s1
	v_mul_hi_i32 v54, v60, s0
	v_lshlrev_b32_e32 v71, 4, v55
	v_lshrrev_b32_e32 v55, 31, v54
	v_ashrrev_i32_e32 v54, 3, v54
	v_add_u32_e32 v54, v54, v55
	v_add_u32_e32 v62, 0x800, v52
	v_mul_lo_u32 v55, v54, 26
	v_sub_u32_e32 v55, v60, v55
	v_mul_lo_u32 v72, v54, s1
	v_mul_hi_i32 v54, v62, s0
	v_lshlrev_b32_e32 v73, 4, v55
	v_lshrrev_b32_e32 v55, 31, v54
	v_ashrrev_i32_e32 v54, 3, v54
	v_add_u32_e32 v54, v54, v55
	v_add_u32_e32 v64, 0xa00, v52
	v_mul_lo_u32 v55, v54, 26
	v_sub_u32_e32 v55, v62, v55
	v_mul_lo_u32 v74, v54, s1
	v_mul_hi_i32 v54, v64, s0
	v_lshlrev_b32_e32 v75, 4, v55
	v_lshrrev_b32_e32 v55, 31, v54
	v_ashrrev_i32_e32 v54, 3, v54
	v_add_u32_e32 v54, v54, v55
	v_mul_lo_u32 v55, v54, 26
	v_sub_u32_e32 v55, v64, v55
	v_mul_lo_u32 v76, v54, s1
	v_add_u32_e32 v54, 0xc00, v52
	v_lshlrev_b32_e32 v77, 4, v55
	v_mul_hi_i32 v55, v54, s0
	v_lshrrev_b32_e32 v78, 31, v55
	v_ashrrev_i32_e32 v55, 3, v55
	v_add_u32_e32 v55, v55, v78
	v_mul_lo_u32 v78, v55, 26
	v_sub_u32_e32 v54, v54, v78
	v_mul_lo_u32 v78, v55, s1
	v_min_i32_e32 v55, 0xcff, v52
	v_lshlrev_b32_e32 v79, 4, v54
	v_mul_hi_i32 v54, v55, s0
	v_lshrrev_b32_e32 v80, 31, v54
	v_ashrrev_i32_e32 v54, 3, v54
	v_add_u32_e32 v54, v54, v80
	v_mul_lo_u32 v80, v54, 26
	v_sub_u32_e32 v55, v55, v80
	v_ashrrev_i32_e32 v111, 4, v53
	v_lshlrev_b32_e32 v116, 3, v55
	v_ashrrev_i32_e32 v55, 31, v54
	v_min_i32_e32 v53, 0xcff, v53
	v_lshlrev_b64 v[88:89], 12, v[54:55]
	v_mul_hi_i32 v54, v53, s0
	v_lshrrev_b32_e32 v55, 31, v54
	v_ashrrev_i32_e32 v54, 3, v54
	v_add_u32_e32 v54, v54, v55
	v_mul_lo_u32 v55, v54, 26
	v_sub_u32_e32 v53, v53, v55
	v_lshlrev_b32_e32 v117, 3, v53
	v_ashrrev_i32_e32 v55, 31, v54
	v_min_i32_e32 v53, 0xcff, v58
	v_lshlrev_b64 v[90:91], 12, v[54:55]
	v_mul_hi_i32 v54, v53, s0
	v_lshrrev_b32_e32 v55, 31, v54
	v_ashrrev_i32_e32 v54, 3, v54
	v_add_u32_e32 v54, v54, v55
	v_mul_lo_u32 v55, v54, 26
	v_sub_u32_e32 v53, v53, v55
	v_lshlrev_b32_e32 v118, 3, v53
	v_ashrrev_i32_e32 v55, 31, v54
	v_min_i32_e32 v53, 0xcff, v60
	v_lshlrev_b64 v[92:93], 12, v[54:55]
	v_mul_hi_i32 v54, v53, s0
	v_lshrrev_b32_e32 v55, 31, v54
	v_ashrrev_i32_e32 v54, 3, v54
	v_add_u32_e32 v54, v54, v55
	v_mul_lo_u32 v55, v54, 26
	v_sub_u32_e32 v53, v53, v55
	v_lshlrev_b32_e32 v119, 3, v53
	v_ashrrev_i32_e32 v55, 31, v54
	v_min_i32_e32 v53, 0xcff, v62
	v_lshlrev_b64 v[94:95], 12, v[54:55]
	v_mul_hi_i32 v54, v53, s0
	v_lshrrev_b32_e32 v55, 31, v54
	v_ashrrev_i32_e32 v54, 3, v54
	v_add_u32_e32 v54, v54, v55
	v_mul_lo_u32 v55, v54, 26
	v_sub_u32_e32 v53, v53, v55
	v_lshlrev_b32_e32 v120, 3, v53
	v_ashrrev_i32_e32 v55, 31, v54
	v_min_i32_e32 v53, 0xcff, v64
	v_lshlrev_b64 v[96:97], 12, v[54:55]
	v_mul_hi_i32 v54, v53, s0
	v_lshrrev_b32_e32 v55, 31, v54
	v_ashrrev_i32_e32 v54, 3, v54
	v_add_u32_e32 v54, v54, v55
	s_movk_i32 s4, 0xb00
	s_movk_i32 s6, 0x900
	s_movk_i32 s8, 0x700
	s_movk_i32 s10, 0x500
	s_movk_i32 s12, 0x300
	s_movk_i32 s14, 0x100
	v_mul_lo_u32 v55, v54, 26
	v_cmp_gt_i32_e64 s[4:5], s4, v52
	v_cmp_gt_i32_e64 s[6:7], s6, v52
	v_cmp_gt_i32_e64 s[8:9], s8, v52
	v_cmp_gt_i32_e64 s[10:11], s10, v52
	v_cmp_gt_i32_e64 s[12:13], s12, v52
	v_cmp_gt_i32_e64 s[14:15], s14, v52
	v_sub_u32_e32 v53, v53, v55
	v_min_i32_e32 v52, 0xff, v52
	v_lshlrev_b32_e32 v121, 3, v53
	v_add_u32_e32 v53, 0xc00, v52
	v_ashrrev_i32_e32 v55, 31, v54
	v_mul_hi_i32 v52, v53, s0
	v_lshlrev_b64 v[98:99], 12, v[54:55]
	v_lshrrev_b32_e32 v54, 31, v52
	v_ashrrev_i32_e32 v52, 3, v52
	v_add_u32_e32 v52, v52, v54
	v_mul_lo_u32 v54, v52, 26
	s_add_u32 s54, s90, 0x32a30000
	s_movk_i32 s53, 0x110
	v_ashrrev_i32_e32 v112, 4, v58
	v_ashrrev_i32_e32 v113, 4, v60
	v_ashrrev_i32_e32 v114, 4, v62
	v_ashrrev_i32_e32 v115, 4, v64
	v_readlane_b32 s16, v249, 10
	v_sub_u32_e32 v53, v53, v54
	s_addc_u32 s55, s91, 0
	v_mul_lo_u32 v56, v110, s53
	v_mul_lo_u32 v57, v111, s53
	v_mul_lo_u32 v59, v112, s53
	v_mul_lo_u32 v61, v113, s53
	v_mul_lo_u32 v63, v114, s53
	v_mul_lo_u32 v65, v115, s53
	v_mov_b32_e32 v85, 0
	v_readlane_b32 s17, v249, 11
	v_lshlrev_b32_e32 v122, 3, v53
	v_ashrrev_i32_e32 v53, 31, v52
	s_add_u32 s58, s90, 0x2a4b0000
	v_lshl_add_u64 v[86:87], s[16:17], 0, v[84:85]
	v_lshlrev_b64 v[100:101], 12, v[52:53]
	s_addc_u32 s59, s91, 0
	v_add_u32_e32 v123, v84, v56
	v_add_u32_e32 v124, v84, v57
	v_add_u32_e32 v125, v84, v59
	v_add_u32_e32 v126, v84, v61
	v_add_u32_e32 v127, v84, v63
	v_add_u32_e32 v128, v84, v65
	s_mov_b32 s60, 0x5040100
	v_add_u32_e32 v129, v66, v67
	v_add_u32_e32 v130, v68, v69
	v_add_u32_e32 v131, v70, v71
	v_add_u32_e32 v132, v72, v73
	v_add_u32_e32 v133, v74, v75
	v_add_u32_e32 v134, v76, v77
	v_add_u32_e32 v135, v78, v79
	s_mov_b32 s1, 0
	s_movk_i32 s61, 0x1500
	s_movk_i32 s62, 0x150
	s_movk_i32 s63, 0x81
	s_movk_i32 s64, 0xff7e
	s_movk_i32 s65, 0x540
	s_movk_i32 s66, 0x6000
	s_movk_i32 s67, 0x6f
	s_movk_i32 s68, 0x5f
	s_movk_i32 s69, 0x4f
	s_mov_b32 s70, 0xfe967699
	s_mov_b32 s71, 0x800000
	s_mov_b32 s72, 0x3f317217
	s_mov_b32 s73, 0x7f800000
	v_mov_b32_e32 v136, 0xff61b1e6
	v_mov_b32_e32 v137, 0x41b17218
	s_waitcnt vmcnt(0)
	s_branch .LBB0_1732

.LBB0_1732:
	s_waitcnt vmcnt(40)
	v_lshrrev_b32_e32 v52, 16, v27
	v_lshrrev_b32_e32 v53, 16, v26
	v_lshrrev_b32_e32 v54, 16, v25
	v_lshrrev_b32_e32 v55, 16, v24
	s_barrier
	ds_write_b128 v123, v[0:3]
	ds_write_b128 v124, v[4:7]
	ds_write_b128 v125, v[8:11]
	ds_write_b128 v126, v[12:15]
	ds_write_b128 v127, v[16:19]
	ds_write_b128 v128, v[20:23]
	s_and_saveexec_b64 s[16:17], s[2:3]
	v_perm_b32 v56, v55, v24, s60
	v_perm_b32 v57, v54, v25, s60
	v_perm_b32 v58, v53, v26, s60
	v_perm_b32 v59, v52, v27, s60
	ds_write_b128 v129, v[56:59] offset:52224
	s_or_b64 exec, exec, s[16:17]
	v_lshrrev_b32_e32 v56, 16, v31
	v_lshrrev_b32_e32 v57, 16, v30
	v_lshrrev_b32_e32 v58, 16, v29
	v_lshrrev_b32_e32 v59, 16, v28
	s_and_saveexec_b64 s[16:17], s[4:5]
	v_perm_b32 v60, v59, v28, s60
	v_perm_b32 v61, v58, v29, s60
	v_perm_b32 v62, v57, v30, s60
	v_perm_b32 v63, v56, v31, s60
	ds_write_b128 v130, v[60:63] offset:52224
	s_or_b64 exec, exec, s[16:17]
	v_lshrrev_b32_e32 v60, 16, v35
	v_lshrrev_b32_e32 v61, 16, v34
	v_lshrrev_b32_e32 v62, 16, v33
	v_lshrrev_b32_e32 v63, 16, v32
	s_and_saveexec_b64 s[16:17], s[6:7]
	v_perm_b32 v64, v63, v32, s60
	v_perm_b32 v65, v62, v33, s60
	v_perm_b32 v66, v61, v34, s60
	v_perm_b32 v67, v60, v35, s60
	ds_write_b128 v131, v[64:67] offset:52224
	s_or_b64 exec, exec, s[16:17]
	v_lshrrev_b32_e32 v64, 16, v39
	v_lshrrev_b32_e32 v65, 16, v38
	v_lshrrev_b32_e32 v66, 16, v37
	v_lshrrev_b32_e32 v67, 16, v36
	s_and_saveexec_b64 s[16:17], s[8:9]
	v_perm_b32 v68, v67, v36, s60
	v_perm_b32 v69, v66, v37, s60
	v_perm_b32 v70, v65, v38, s60
	v_perm_b32 v71, v64, v39, s60
	ds_write_b128 v132, v[68:71] offset:52224
	s_or_b64 exec, exec, s[16:17]
	v_lshrrev_b32_e32 v68, 16, v43
	v_lshrrev_b32_e32 v69, 16, v42
	v_lshrrev_b32_e32 v70, 16, v41
	v_lshrrev_b32_e32 v71, 16, v40
	s_and_saveexec_b64 s[16:17], s[10:11]
	v_perm_b32 v72, v71, v40, s60
	v_perm_b32 v73, v70, v41, s60
	v_perm_b32 v74, v69, v42, s60
	v_perm_b32 v75, v68, v43, s60
	ds_write_b128 v133, v[72:75] offset:52224
	s_or_b64 exec, exec, s[16:17]
	v_lshrrev_b32_e32 v72, 16, v47
	v_lshrrev_b32_e32 v73, 16, v46
	v_lshrrev_b32_e32 v74, 16, v45
	v_lshrrev_b32_e32 v75, 16, v44
	s_and_saveexec_b64 s[16:17], s[12:13]
	v_perm_b32 v76, v75, v44, s60
	v_perm_b32 v77, v74, v45, s60
	v_perm_b32 v78, v73, v46, s60
	v_perm_b32 v79, v72, v47, s60
	ds_write_b128 v134, v[76:79] offset:52224
	s_or_b64 exec, exec, s[16:17]
	v_lshrrev_b32_e32 v76, 16, v51
	v_lshrrev_b32_e32 v77, 16, v50
	v_lshrrev_b32_e32 v78, 16, v49
	v_lshrrev_b32_e32 v79, 16, v48
	s_and_saveexec_b64 s[16:17], s[14:15]
	v_perm_b32 v80, v79, v48, s60
	v_perm_b32 v81, v78, v49, s60
	v_perm_b32 v82, v77, v50, s60
	v_perm_b32 v83, v76, v51, s60
	ds_write_b128 v135, v[80:83] offset:52224
	s_or_b64 exec, exec, s[16:17]
	s_add_i32 s74, s36, s52
	s_cmp_ge_i32 s74, s33
	s_cselect_b64 s[48:49], -1, 0
	s_and_b64 vcc, exec, s[48:49]
	s_waitcnt lgkmcnt(0)
	s_barrier
	s_cbranch_vccnz .LBB0_1748
	s_add_i32 s0, s74, 0xffffff40
	s_ashr_i32 s0, s0, 5
	s_mul_hi_i32 s17, s0, 0x55555556
	s_lshr_b32 s18, s17, 31
	s_add_i32 s18, s17, s18
	s_mul_i32 s17, s18, 3
	s_sub_i32 s0, s0, s17
	s_lshl_b32 s20, s0, 1
	s_lshr_b32 s17, 32, s20
	s_and_b32 s16, s74, 31
	s_sub_i32 s22, 5, s20
	s_add_i32 s17, s17, -1
	s_lshr_b32 s22, s16, s22
	s_and_b32 s16, s17, s16
	s_lshl_b32 s23, s16, 6
	s_lshl_b32 s0, s0, 5
	s_and_b32 s16, s18, -8
	s_and_b32 s19, s18, 7
	s_add_i32 s0, s0, s16
	s_or_b32 s16, s0, s19
	s_lshl_b32 s0, s18, 8
	s_ashr_i32 s17, s16, 31
	s_and_b32 s0, s0, 0xfffff800
	s_lshr_b32 s21, 0x800, s20
	s_lshl_b64 s[16:17], s[16:17], 19
	s_addk_i32 s23, 0xff80
	s_or_b32 s18, s22, s0
	s_lshl_b32 s0, s19, 8
	s_mul_i32 s24, s22, s21
	v_lshl_add_u64 v[16:17], v[86:87], 0, s[0:1]
	s_add_u32 s0, s85, s16
	s_addc_u32 s17, s86, s17
	s_lshl_b32 s16, s24, 1
	s_add_u32 s16, s0, s16
	v_add_u32_e32 v24, s23, v116
	v_add_u32_e32 v32, s23, v118
	v_add_u32_e32 v40, s23, v120
	s_addc_u32 s17, s17, 0
	s_add_i32 s21, s21, -8
	v_max_i32_e32 v24, 0, v24
	v_max_i32_e32 v32, 0, v32
	v_max_i32_e32 v40, 0, v40
	v_add_u32_e32 v0, s23, v110
	v_add_u32_e32 v2, s23, v111
	v_add_u32_e32 v8, s23, v112
	v_add_u32_e32 v10, s23, v113
	v_add_u32_e32 v18, s23, v114
	v_add_u32_e32 v20, s23, v115
	v_min_i32_e32 v24, s21, v24
	v_min_i32_e32 v32, s21, v32
	v_min_i32_e32 v40, s21, v40
	v_max_i32_e32 v0, 0, v0
	v_max_i32_e32 v2, 0, v2
	v_max_i32_e32 v8, 0, v8
	v_max_i32_e32 v10, 0, v10
	v_max_i32_e32 v18, 0, v18
	v_max_i32_e32 v20, 0, v20
	v_lshl_add_u64 v[26:27], s[16:17], 0, v[88:89]
	v_ashrrev_i32_e32 v25, 31, v24
	v_lshl_add_u64 v[34:35], s[16:17], 0, v[92:93]
	v_ashrrev_i32_e32 v33, 31, v32
	v_lshl_add_u64 v[42:43], s[16:17], 0, v[96:97]
	v_ashrrev_i32_e32 v41, 31, v40
	v_lshlrev_b32_e32 v0, s20, v0
	v_lshlrev_b32_e32 v2, s20, v2
	v_lshlrev_b32_e32 v8, s20, v8
	v_lshlrev_b32_e32 v10, s20, v10
	v_lshlrev_b32_e32 v18, s20, v18
	v_lshlrev_b32_e32 v20, s20, v20
	v_lshl_add_u64 v[24:25], v[24:25], 1, v[26:27]
	v_add_u32_e32 v26, s23, v117
	v_lshl_add_u64 v[32:33], v[32:33], 1, v[34:35]
	v_add_u32_e32 v34, s23, v119
	v_lshl_add_u64 v[40:41], v[40:41], 1, v[42:43]
	v_add_u32_e32 v42, s23, v121
	v_add_u32_e32 v48, s23, v122
	v_add_u32_e32 v0, s18, v0
	v_add_u32_e32 v2, s18, v2
	v_add_u32_e32 v8, s18, v8
	v_add_u32_e32 v10, s18, v10
	v_add_u32_e32 v18, s18, v18
	v_add_u32_e32 v20, s18, v20
	v_max_i32_e32 v26, 0, v26
	v_max_i32_e32 v34, 0, v34
	v_max_i32_e32 v42, 0, v42
	v_max_i32_e32 v48, 0, v48
	v_ashrrev_i32_e32 v1, 31, v0
	v_ashrrev_i32_e32 v3, 31, v2
	v_ashrrev_i32_e32 v9, 31, v8
	v_ashrrev_i32_e32 v11, 31, v10
	v_ashrrev_i32_e32 v19, 31, v18
	v_ashrrev_i32_e32 v21, 31, v20
	v_min_i32_e32 v26, s21, v26
	v_min_i32_e32 v34, s21, v34
	v_min_i32_e32 v42, s21, v42
	v_min_i32_e32 v48, s21, v48
	v_lshlrev_b64 v[0:1], 11, v[0:1]
	v_lshlrev_b64 v[2:3], 11, v[2:3]
	v_lshlrev_b64 v[8:9], 11, v[8:9]
	v_lshlrev_b64 v[10:11], 11, v[10:11]
	v_lshlrev_b64 v[18:19], 11, v[18:19]
	v_lshlrev_b64 v[20:21], 11, v[20:21]
	v_lshl_add_u64 v[28:29], s[16:17], 0, v[90:91]
	v_ashrrev_i32_e32 v27, 31, v26
	v_lshl_add_u64 v[36:37], s[16:17], 0, v[94:95]
	v_ashrrev_i32_e32 v35, 31, v34
	v_lshl_add_u64 v[44:45], s[16:17], 0, v[98:99]
	v_ashrrev_i32_e32 v43, 31, v42
	v_lshl_add_u64 v[50:51], s[16:17], 0, v[100:101]
	v_ashrrev_i32_e32 v49, 31, v48
	v_lshl_add_u64 v[0:1], v[16:17], 0, v[0:1]
	v_lshl_add_u64 v[4:5], v[16:17], 0, v[2:3]
	v_lshl_add_u64 v[8:9], v[16:17], 0, v[8:9]
	v_lshl_add_u64 v[12:13], v[16:17], 0, v[10:11]
	v_lshl_add_u64 v[18:19], v[16:17], 0, v[18:19]
	v_lshl_add_u64 v[20:21], v[16:17], 0, v[20:21]
	v_lshl_add_u64 v[28:29], v[26:27], 1, v[28:29]
	v_lshl_add_u64 v[36:37], v[34:35], 1, v[36:37]
	v_lshl_add_u64 v[44:45], v[42:43], 1, v[44:45]
	v_lshl_add_u64 v[48:49], v[48:49], 1, v[50:51]
	s_branch .LBB0_1749

.LBB0_1751:
	v_or_b32_e32 v52, s38, v139
	v_or_b32_e32 v108, s75, v52
	s_and_b64 vcc, exec, s[50:51]
	s_nop 0
	s_cbranch_vccz .Lq_rb1
	v_or_b32_e32 v53, v108, v138
	v_lshlrev_b32_e32 v53, s0, v53
	v_add_u32_e32 v53, s76, v53
	v_mad_i64_i32 v[66:67], s[38:39], v53, s66, v[102:103]
	global_load_dwordx4 v[54:57], v[66:67], off
	global_load_dwordx4 v[58:61], v[66:67], off offset:64
	global_load_dwordx4 v[62:65], v[66:67], off offset:128
	s_nop 0
	global_load_dwordx4 v[66:69], v[66:67], off offset:192
	v_or_b32_e32 v212, 16, v108
	v_or_b32_e32 v212, v212, v138
	v_lshlrev_b32_e32 v212, s0, v212
	v_add_u32_e32 v212, s76, v212
	v_mad_i64_i32 v[210:211], s[38:39], v212, s66, v[102:103]
	global_load_dwordx4 v[194:197], v[210:211], off
	global_load_dwordx4 v[198:201], v[210:211], off offset:64
	global_load_dwordx4 v[202:205], v[210:211], off offset:128
	global_load_dwordx4 v[206:209], v[210:211], off offset:192
	s_and_b64 vcc, exec, s[48:49]
	s_nop 0
	s_cbranch_vccnz .Lq_last
	global_load_dwordx4 v[0:3], v[0:1], off
	s_nop 0
	global_load_dwordx4 v[4:7], v[4:5], off
	s_nop 0
	global_load_dwordx4 v[8:11], v[8:9], off
	s_nop 0
	global_load_dwordx4 v[12:15], v[12:13], off
	s_nop 0
	global_load_dwordx4 v[16:19], v[18:19], off
	s_nop 0
	global_load_dwordx4 v[20:23], v[20:21], off
	s_nop 0
	global_load_dwordx4 v[24:27], v[24:25], off
	s_nop 0
	global_load_dwordx4 v[28:31], v[28:29], off
	s_nop 0
	global_load_dwordx4 v[32:35], v[32:33], off
	s_nop 0
	global_load_dwordx4 v[36:39], v[36:37], off
	s_nop 0
	global_load_dwordx4 v[40:43], v[40:41], off
	s_nop 0
	global_load_dwordx4 v[44:47], v[44:45], off
	s_nop 0
	global_load_dwordx4 v[48:51], v[48:49], off
	s_waitcnt vmcnt(17)
	s_branch .Lq_go
.Lq_last:
	s_waitcnt vmcnt(4)
	s_branch .Lq_go
.Lq_rb1:
	s_waitcnt vmcnt(32)
	v_mov_b32_e32 v54, v194
	v_mov_b32_e32 v55, v195
	v_mov_b32_e32 v56, v196
	v_mov_b32_e32 v57, v197
	v_mov_b32_e32 v58, v198
	v_mov_b32_e32 v59, v199
	v_mov_b32_e32 v60, v200
	v_mov_b32_e32 v61, v201
	v_mov_b32_e32 v62, v202
	v_mov_b32_e32 v63, v203
	v_mov_b32_e32 v64, v204
	v_mov_b32_e32 v65, v205
	v_mov_b32_e32 v66, v206
	v_mov_b32_e32 v67, v207
	v_mov_b32_e32 v68, v208
	v_mov_b32_e32 v69, v209
.Lq_go:
	s_setprio 1
	v_or_b32_e32 v53, v52, v138
	v_mad_u32_u24 v53, v53, s53, v84
	ds_read_b128 v[70:73], v53
	ds_read_b128 v[74:77], v53 offset:64
	ds_read_b128 v[78:81], v53 offset:4352
	ds_read_b128 v[146:149], v53 offset:4416
	s_waitcnt lgkmcnt(3)
	v_mfma_f32_16x16x32_bf16 v[70:73], v[54:57], v[70:73], 0
	s_waitcnt lgkmcnt(1)
	v_mfma_f32_16x16x32_bf16 v[78:81], v[54:57], v[78:81], 0
	v_mfma_f32_16x16x32_bf16 v[70:73], v[58:61], v[74:77], v[70:73]
	ds_read_b128 v[74:77], v53 offset:128
	ds_read_b128 v[150:153], v53 offset:192
	s_waitcnt lgkmcnt(1)
	v_mfma_f32_16x16x32_bf16 v[70:73], v[62:65], v[74:77], v[70:73]
	v_mfma_f32_16x16x32_bf16 v[74:77], v[58:61], v[146:149], v[78:81]
	s_nop 2
	ds_read_b128 v[78:81], v53 offset:4480
	ds_read_b128 v[146:149], v53 offset:4544
	s_waitcnt lgkmcnt(1)
	v_mfma_f32_16x16x32_bf16 v[74:77], v[62:65], v[78:81], v[74:77]
	s_waitcnt lgkmcnt(0)
	v_mfma_f32_16x16x32_bf16 v[74:77], v[66:69], v[146:149], v[74:77]
	ds_read_b128 v[78:81], v53 offset:8704
	ds_read_b128 v[146:149], v53 offset:8768
	s_waitcnt lgkmcnt(1)
	v_mfma_f32_16x16x32_bf16 v[78:81], v[54:57], v[78:81], 0
	v_mfma_f32_16x16x32_bf16 v[70:73], v[66:69], v[150:153], v[70:73]
	s_waitcnt lgkmcnt(0)
	v_mfma_f32_16x16x32_bf16 v[78:81], v[58:61], v[146:149], v[78:81]
	ds_read_b128 v[146:149], v53 offset:8832
	ds_read_b128 v[150:153], v53 offset:8896
	s_waitcnt lgkmcnt(1)
	v_mfma_f32_16x16x32_bf16 v[78:81], v[62:65], v[146:149], v[78:81]
	s_waitcnt lgkmcnt(0)
	v_mfma_f32_16x16x32_bf16 v[78:81], v[66:69], v[150:153], v[78:81]
	ds_read_b128 v[146:149], v53 offset:13056
	ds_read_b128 v[150:153], v53 offset:13120
	s_waitcnt lgkmcnt(1)
	v_mfma_f32_16x16x32_bf16 v[146:149], v[54:57], v[146:149], 0
	s_waitcnt lgkmcnt(0)
	v_mfma_f32_16x16x32_bf16 v[146:149], v[58:61], v[150:153], v[146:149]
	ds_read_b128 v[150:153], v53 offset:13184
	ds_read_b128 v[154:157], v53 offset:13248
	s_waitcnt lgkmcnt(1)
	v_mfma_f32_16x16x32_bf16 v[146:149], v[62:65], v[150:153], v[146:149]
	s_waitcnt lgkmcnt(0)
	v_mfma_f32_16x16x32_bf16 v[148:151], v[66:69], v[154:157], v[146:149]
	ds_read_b128 v[152:155], v53 offset:17408
	ds_read_b128 v[156:159], v53 offset:17472
	s_waitcnt lgkmcnt(1)
	v_mfma_f32_16x16x32_bf16 v[152:155], v[54:57], v[152:155], 0
	s_waitcnt lgkmcnt(0)
	v_mfma_f32_16x16x32_bf16 v[152:155], v[58:61], v[156:159], v[152:155]
	ds_read_b128 v[156:159], v53 offset:17536
	ds_read_b128 v[160:163], v53 offset:17600
	s_waitcnt lgkmcnt(1)
	v_mfma_f32_16x16x32_bf16 v[152:155], v[62:65], v[156:159], v[152:155]
	s_waitcnt lgkmcnt(0)
	v_mfma_f32_16x16x32_bf16 v[152:155], v[66:69], v[160:163], v[152:155]
	ds_read_b128 v[156:159], v53 offset:21760
	ds_read_b128 v[160:163], v53 offset:21824
	s_waitcnt lgkmcnt(1)
	v_mfma_f32_16x16x32_bf16 v[156:159], v[54:57], v[156:159], 0
	s_waitcnt lgkmcnt(0)
	v_mfma_f32_16x16x32_bf16 v[156:159], v[58:61], v[160:163], v[156:159]
	ds_read_b128 v[160:163], v53 offset:21888
	ds_read_b128 v[164:167], v53 offset:21952
	s_waitcnt lgkmcnt(1)
	v_mfma_f32_16x16x32_bf16 v[156:159], v[62:65], v[160:163], v[156:159]
	s_waitcnt lgkmcnt(0)
	v_mfma_f32_16x16x32_bf16 v[156:159], v[66:69], v[164:167], v[156:159]
	ds_read_b128 v[160:163], v53 offset:26112
	ds_read_b128 v[164:167], v53 offset:26176
	s_waitcnt lgkmcnt(1)
	v_mfma_f32_16x16x32_bf16 v[160:163], v[54:57], v[160:163], 0
	s_waitcnt lgkmcnt(0)
	v_mfma_f32_16x16x32_bf16 v[160:163], v[58:61], v[164:167], v[160:163]
	ds_read_b128 v[164:167], v53 offset:26240
	ds_read_b128 v[168:171], v53 offset:26304
	s_waitcnt lgkmcnt(1)
	v_mfma_f32_16x16x32_bf16 v[160:163], v[62:65], v[164:167], v[160:163]
	s_waitcnt lgkmcnt(0)
	v_mfma_f32_16x16x32_bf16 v[160:163], v[66:69], v[168:171], v[160:163]
	ds_read_b128 v[164:167], v53 offset:30464
	ds_read_b128 v[168:171], v53 offset:30528
	s_waitcnt lgkmcnt(1)
	v_mfma_f32_16x16x32_bf16 v[164:167], v[54:57], v[164:167], 0
	s_waitcnt lgkmcnt(0)
	v_mfma_f32_16x16x32_bf16 v[164:167], v[58:61], v[168:171], v[164:167]
	ds_read_b128 v[168:171], v53 offset:30592
	ds_read_b128 v[172:175], v53 offset:30656
	s_waitcnt lgkmcnt(1)
	v_mfma_f32_16x16x32_bf16 v[164:167], v[62:65], v[168:171], v[164:167]
	s_waitcnt lgkmcnt(0)
	v_mfma_f32_16x16x32_bf16 v[164:167], v[66:69], v[172:175], v[164:167]
	ds_read_b128 v[168:171], v53 offset:34816
	ds_read_b128 v[172:175], v53 offset:34880
	s_waitcnt lgkmcnt(1)
	v_mfma_f32_16x16x32_bf16 v[54:57], v[54:57], v[168:171], 0
	s_waitcnt lgkmcnt(0)
	v_mfma_f32_16x16x32_bf16 v[54:57], v[58:61], v[172:175], v[54:57]
	ds_read_b128 v[58:61], v53 offset:34944
	ds_read_b128 v[168:171], v53 offset:35008
	s_waitcnt lgkmcnt(1)
	v_mfma_f32_16x16x32_bf16 v[54:57], v[62:65], v[58:61], v[54:57]
	s_waitcnt lgkmcnt(0)
	v_mfma_f32_16x16x32_bf16 v[54:57], v[66:69], v[168:171], v[54:57]
	s_setprio 0
	v_cndmask_b32_e64 v53, v136, v70, s[26:27]
	v_max_f32_e32 v58, v53, v53
	v_cmp_lt_u32_e32 vcc, s67, v108
	v_cmp_lt_u32_e64 s[38:39], s68, v108
	v_max_f32_e32 v58, 0xff61b1e6, v58
	v_cndmask_b32_e32 v59, v136, v74, vcc
	v_cndmask_b32_e64 v60, v136, v78, s[38:39]
	v_cmp_lt_u32_e64 s[40:41], s69, v108
	v_max3_f32 v58, v58, v59, v60
	v_cndmask_b32_e64 v62, v152, v136, s[28:29]
	v_cndmask_b32_e64 v61, v136, v148, s[40:41]
	v_cmp_lt_u32_e64 s[42:43], 47, v108
	v_cmp_lt_u32_e64 s[44:45], 31, v108
	v_max3_f32 v58, v58, v61, v62
	v_cndmask_b32_e64 v63, v136, v156, s[42:43]
	v_cndmask_b32_e64 v64, v136, v160, s[44:45]
	v_cmp_eq_u32_e64 s[46:47], 0, v108
	v_max3_f32 v58, v58, v63, v64
	v_cndmask_b32_e64 v54, v136, v54, s[18:19]
	v_cndmask_b32_e64 v65, v164, v136, s[46:47]
	v_max3_f32 v58, v58, v65, v54
	v_mov_b32_e32 v66, v58
	v_cndmask_b32_e32 v67, v136, v75, vcc
	v_cndmask_b32_e64 v68, v136, v79, s[38:39]
	v_mov_b32_dpp v66, v66 quad_perm:[1,0,3,2] row_mask:0xf bank_mask:0xf
	v_max_f32_e32 v66, v66, v66
	v_max_f32_e32 v58, v58, v66
	v_mov_b32_e32 v66, v58
	v_cndmask_b32_e64 v69, v136, v149, s[40:41]
	v_cndmask_b32_e64 v70, v153, v136, s[28:29]
	v_mov_b32_dpp v66, v66 quad_perm:[2,3,0,1] row_mask:0xf bank_mask:0xf
	v_max_f32_e32 v66, v66, v66
	v_max_f32_e32 v58, v58, v66
	v_mov_b32_e32 v66, v58
	v_cndmask_b32_e64 v74, v136, v161, s[44:45]
	v_cndmask_b32_e64 v75, v165, v136, s[46:47]
	v_mov_b32_dpp v66, v66 row_half_mirror row_mask:0xf bank_mask:0xf
	v_max_f32_e32 v66, v66, v66
	v_max_f32_e32 v58, v58, v66
	v_mov_b32_e32 v66, v58
	v_cndmask_b32_e64 v55, v136, v55, s[20:21]
	v_cndmask_b32_e32 v76, v136, v76, vcc
	v_mov_b32_dpp v66, v66 row_mirror row_mask:0xf bank_mask:0xf
	v_max_f32_e32 v66, v66, v66
	v_max_f32_e32 v148, v58, v66
	v_cndmask_b32_e64 v58, v136, v71, s[30:31]
	v_max_f32_e32 v66, v58, v58
	v_max_f32_e32 v66, 0xff61b1e6, v66
	v_max3_f32 v66, v66, v67, v68
	v_max3_f32 v66, v66, v69, v70
	v_cndmask_b32_e64 v71, v136, v157, s[42:43]
	v_max3_f32 v66, v66, v71, v74
	v_max3_f32 v66, v66, v75, v55
	v_mov_b32_e32 v78, v66
	v_cndmask_b32_e64 v79, v136, v150, s[40:41]
	v_cndmask_b32_e64 v82, v136, v158, s[42:43]
	v_mov_b32_dpp v78, v78 quad_perm:[1,0,3,2] row_mask:0xf bank_mask:0xf
	v_max_f32_e32 v78, v78, v78
	v_max_f32_e32 v66, v66, v78
	v_mov_b32_e32 v78, v66
	v_cndmask_b32_e64 v83, v136, v162, s[44:45]
	v_cndmask_b32_e64 v109, v166, v136, s[46:47]
	v_mov_b32_dpp v78, v78 quad_perm:[2,3,0,1] row_mask:0xf bank_mask:0xf
	v_max_f32_e32 v78, v78, v78
	v_max_f32_e32 v66, v66, v78
	v_mov_b32_e32 v78, v66
	v_cndmask_b32_e64 v56, v136, v56, s[22:23]
	v_sub_f32_e32 v149, v53, v148
	v_mov_b32_dpp v78, v78 row_half_mirror row_mask:0xf bank_mask:0xf
	v_max_f32_e32 v78, v78, v78
	v_max_f32_e32 v66, v66, v78
	v_mov_b32_e32 v78, v66
	v_mul_f32_e32 v149, 0x3fb8aa3b, v149
	v_exp_f32_e32 v149, v149
	v_mov_b32_dpp v78, v78 row_mirror row_mask:0xf bank_mask:0xf
	v_max_f32_e32 v78, v78, v78
	v_max_f32_e32 v147, v66, v78
	v_cndmask_b32_e64 v66, v136, v72, s[34:35]
	v_max_f32_e32 v72, v66, v66
	v_max_f32_e32 v72, 0xff61b1e6, v72
	v_cndmask_b32_e64 v78, v136, v80, s[38:39]
	v_max3_f32 v72, v72, v76, v78
	v_cndmask_b32_e64 v80, v154, v136, s[28:29]
	v_max3_f32 v72, v72, v79, v80
	v_max3_f32 v72, v72, v82, v83
	v_max3_f32 v72, v72, v109, v56
	v_mov_b32_e32 v145, v72
	v_cndmask_b32_e32 v77, v136, v77, vcc
	v_cmp_lt_f32_e32 vcc, s70, v53
	v_mov_b32_dpp v145, v145 quad_perm:[1,0,3,2] row_mask:0xf bank_mask:0xf
	v_max_f32_e32 v145, v145, v145
	v_max_f32_e32 v72, v72, v145
	v_mov_b32_e32 v145, v72
	v_cndmask_b32_e32 v53, 0, v149, vcc
	v_sub_f32_e32 v149, v59, v148
	v_mov_b32_dpp v145, v145 quad_perm:[2,3,0,1] row_mask:0xf bank_mask:0xf
	v_max_f32_e32 v145, v145, v145
	v_max_f32_e32 v72, v72, v145
	v_mov_b32_e32 v145, v72
	v_mul_f32_e32 v149, 0x3fb8aa3b, v149
	v_sub_f32_e32 v150, v60, v148
	v_mov_b32_dpp v145, v145 row_half_mirror row_mask:0xf bank_mask:0xf
	v_max_f32_e32 v145, v145, v145
	v_exp_f32_e32 v149, v149
	v_mul_f32_e32 v150, 0x3fb8aa3b, v150
	v_max_f32_e32 v72, v72, v145
	v_exp_f32_e32 v150, v150
	v_mov_b32_e32 v145, v72
	v_cmp_lt_f32_e32 vcc, s70, v59
	v_cndmask_b32_e64 v81, v136, v81, s[38:39]
	v_mov_b32_dpp v145, v145 row_mirror row_mask:0xf bank_mask:0xf
	v_max_f32_e32 v145, v145, v145
	v_cndmask_b32_e32 v59, 0, v149, vcc
	v_cmp_lt_f32_e32 vcc, s70, v60
	v_sub_f32_e32 v149, v61, v148
	v_max_f32_e32 v146, v72, v145
	v_cndmask_b32_e64 v72, v136, v73, s[36:37]
	v_cndmask_b32_e32 v60, 0, v150, vcc
	v_mul_f32_e32 v149, 0x3fb8aa3b, v149
	v_sub_f32_e32 v150, v62, v148
	v_max_f32_e32 v73, v72, v72
	v_exp_f32_e32 v149, v149
	v_mul_f32_e32 v150, 0x3fb8aa3b, v150
	v_max_f32_e32 v73, 0xff61b1e6, v73
	v_exp_f32_e32 v150, v150
	v_max3_f32 v73, v73, v77, v81
	v_cndmask_b32_e64 v152, v136, v151, s[40:41]
	v_cndmask_b32_e64 v153, v155, v136, s[28:29]
	v_max3_f32 v73, v73, v152, v153
	v_cndmask_b32_e64 v156, v136, v159, s[42:43]
	v_cndmask_b32_e64 v157, v136, v163, s[44:45]
	v_cmp_lt_f32_e32 vcc, s70, v61
	v_max3_f32 v73, v73, v156, v157
	v_cndmask_b32_e64 v158, v167, v136, s[46:47]
	v_cndmask_b32_e64 v57, v136, v57, s[24:25]
	v_cndmask_b32_e32 v61, 0, v149, vcc
	v_cmp_lt_f32_e32 vcc, s70, v62
	v_sub_f32_e32 v149, v63, v148
	v_max3_f32 v73, v73, v158, v57
	v_cndmask_b32_e32 v62, 0, v150, vcc
	v_mul_f32_e32 v149, 0x3fb8aa3b, v149
	v_sub_f32_e32 v150, v64, v148
	v_mov_b32_e32 v145, v73
	v_exp_f32_e32 v149, v149
	v_mul_f32_e32 v150, 0x3fb8aa3b, v150
	v_mov_b32_dpp v145, v145 quad_perm:[1,0,3,2] row_mask:0xf bank_mask:0xf
	v_exp_f32_e32 v150, v150
	v_max_f32_e32 v145, v145, v145
	v_max_f32_e32 v73, v73, v145
	v_cmp_lt_f32_e32 vcc, s70, v63
	v_mov_b32_e32 v145, v73
	v_sub_f32_e32 v151, v68, v147
	v_cndmask_b32_e32 v63, 0, v149, vcc
	v_cmp_lt_f32_e32 vcc, s70, v64
	v_sub_f32_e32 v149, v65, v148
	v_mov_b32_dpp v145, v145 quad_perm:[2,3,0,1] row_mask:0xf bank_mask:0xf
	v_cndmask_b32_e32 v64, 0, v150, vcc
	v_mul_f32_e32 v149, 0x3fb8aa3b, v149
	v_sub_f32_e32 v150, v54, v148
	v_max_f32_e32 v145, v145, v145
	v_exp_f32_e32 v149, v149
	v_mul_f32_e32 v150, 0x3fb8aa3b, v150
	v_max_f32_e32 v73, v73, v145
	v_exp_f32_e32 v150, v150
	v_mov_b32_e32 v145, v73
	v_cmp_lt_f32_e32 vcc, s70, v65
	v_mul_f32_e32 v151, 0x3fb8aa3b, v151
	v_mov_b32_dpp v145, v145 row_half_mirror row_mask:0xf bank_mask:0xf
	v_max_f32_e32 v145, v145, v145
	v_cndmask_b32_e32 v65, 0, v149, vcc
	v_cmp_lt_f32_e32 vcc, s70, v54
	v_max_f32_e32 v73, v73, v145
	v_mov_b32_e32 v145, v73
	v_cndmask_b32_e32 v54, 0, v150, vcc
	v_sub_f32_e32 v150, v58, v147
	v_mul_f32_e32 v150, 0x3fb8aa3b, v150
	v_mov_b32_dpp v145, v145 row_mirror row_mask:0xf bank_mask:0xf
	v_exp_f32_e32 v150, v150
	v_max_f32_e32 v145, v145, v145
	v_max_f32_e32 v145, v73, v145
	v_add_f32_e32 v73, 0, v53
	v_add_f32_e32 v73, v59, v73
	v_cmp_lt_f32_e32 vcc, s70, v58
	v_add_f32_e32 v73, v60, v73
	v_add_f32_e32 v73, v61, v73
	v_cndmask_b32_e32 v58, 0, v150, vcc
	v_sub_f32_e32 v150, v67, v147
	v_mul_f32_e32 v150, 0x3fb8aa3b, v150
	v_add_f32_e32 v73, v62, v73
	v_exp_f32_e32 v150, v150
	v_add_f32_e32 v73, v63, v73
	v_exp_f32_e32 v151, v151
	v_add_f32_e32 v73, v64, v73
	v_add_f32_e32 v73, v65, v73
	v_cmp_lt_f32_e32 vcc, s70, v67
	v_add_f32_e32 v73, v54, v73
	v_mov_b32_e32 v149, v73
	v_cndmask_b32_e32 v67, 0, v150, vcc
	v_cmp_lt_f32_e32 vcc, s70, v68
	v_sub_f32_e32 v150, v69, v147
	v_mul_f32_e32 v150, 0x3fb8aa3b, v150
	v_cndmask_b32_e32 v68, 0, v151, vcc
	v_sub_f32_e32 v151, v70, v147
	v_mov_b32_dpp v149, v149 quad_perm:[1,0,3,2] row_mask:0xf bank_mask:0xf
	v_exp_f32_e32 v150, v150
	v_mul_f32_e32 v151, 0x3fb8aa3b, v151
	v_add_f32_e32 v73, v73, v149
	v_exp_f32_e32 v151, v151
	v_mov_b32_e32 v149, v73
	v_cmp_lt_f32_e32 vcc, s70, v69
	v_sub_f32_e32 v155, v78, v146
	v_mov_b32_dpp v149, v149 quad_perm:[2,3,0,1] row_mask:0xf bank_mask:0xf
	v_add_f32_e32 v73, v73, v149
	v_cndmask_b32_e32 v69, 0, v150, vcc
	v_cmp_lt_f32_e32 vcc, s70, v70
	v_sub_f32_e32 v150, v71, v147
	v_mov_b32_e32 v149, v73
	v_cndmask_b32_e32 v70, 0, v151, vcc
	v_mul_f32_e32 v150, 0x3fb8aa3b, v150
	v_sub_f32_e32 v151, v74, v147
	v_mov_b32_dpp v149, v149 row_half_mirror row_mask:0xf bank_mask:0xf
	v_exp_f32_e32 v150, v150
	v_mul_f32_e32 v151, 0x3fb8aa3b, v151
	v_add_f32_e32 v73, v73, v149
	v_exp_f32_e32 v151, v151
	v_mov_b32_e32 v149, v73
	v_cmp_lt_f32_e32 vcc, s70, v71
	v_mul_f32_e32 v155, 0x3fb8aa3b, v155
	v_mov_b32_dpp v149, v149 row_mirror row_mask:0xf bank_mask:0xf
	v_add_f32_e32 v149, v73, v149
	v_add_f32_e32 v73, 0, v58
	v_cndmask_b32_e32 v71, 0, v150, vcc
	v_cmp_lt_f32_e32 vcc, s70, v74
	v_sub_f32_e32 v150, v75, v147
	v_add_f32_e32 v73, v67, v73
	v_cndmask_b32_e32 v74, 0, v151, vcc
	v_mul_f32_e32 v150, 0x3fb8aa3b, v150
	v_sub_f32_e32 v151, v55, v147
	v_add_f32_e32 v73, v68, v73
	v_exp_f32_e32 v150, v150
	v_mul_f32_e32 v151, 0x3fb8aa3b, v151
	v_add_f32_e32 v73, v69, v73
	v_exp_f32_e32 v151, v151
	v_add_f32_e32 v73, v70, v73
	v_add_f32_e32 v73, v71, v73
	v_cmp_lt_f32_e32 vcc, s70, v75
	v_add_f32_e32 v73, v74, v73
	v_exp_f32_e32 v155, v155
	v_cndmask_b32_e32 v75, 0, v150, vcc
	v_cmp_lt_f32_e32 vcc, s70, v55
	v_add_f32_e32 v73, v75, v73
	v_cvt_pk_bf16_f32 v53, v53, s0
	v_cndmask_b32_e32 v55, 0, v151, vcc
	v_add_f32_e32 v73, v55, v73
	v_mov_b32_e32 v150, v73
	v_sub_f32_e32 v151, v76, v146
	v_mul_f32_e32 v151, 0x3fb8aa3b, v151
	v_mov_b32_dpp v150, v150 quad_perm:[1,0,3,2] row_mask:0xf bank_mask:0xf
	v_add_f32_e32 v73, v73, v150
	v_mov_b32_e32 v150, v73
	v_exp_f32_e32 v151, v151
	v_cmp_lt_f32_e32 vcc, s70, v66
	v_mov_b32_dpp v150, v150 quad_perm:[2,3,0,1] row_mask:0xf bank_mask:0xf
	v_add_f32_e32 v73, v73, v150
	v_mov_b32_e32 v150, v73
	ds_write_b16 v142, v53
	v_cvt_pk_bf16_f32 v53, v59, s0
	v_mov_b32_dpp v150, v150 row_half_mirror row_mask:0xf bank_mask:0xf
	v_add_f32_e32 v150, v73, v150
	v_sub_f32_e32 v73, v66, v146
	v_mul_f32_e32 v73, 0x3fb8aa3b, v73
	v_exp_f32_e32 v73, v73
	ds_write_b16 v142, v53 offset:32
	v_cvt_pk_bf16_f32 v53, v60, s0
	v_sub_f32_e32 v159, v77, v145
	v_cndmask_b32_e32 v66, 0, v73, vcc
	v_cmp_lt_f32_e32 vcc, s70, v76
	v_add_f32_e32 v73, 0, v66
	ds_write_b16 v142, v53 offset:64
	v_cndmask_b32_e32 v76, 0, v151, vcc
	v_cmp_lt_f32_e32 vcc, s70, v78
	v_sub_f32_e32 v151, v79, v146
	v_mul_f32_e32 v151, 0x3fb8aa3b, v151
	v_cndmask_b32_e32 v78, 0, v155, vcc
	v_sub_f32_e32 v155, v80, v146
	v_exp_f32_e32 v151, v151
	v_mul_f32_e32 v155, 0x3fb8aa3b, v155
	v_exp_f32_e32 v155, v155
	v_cmp_lt_f32_e32 vcc, s70, v79
	v_add_f32_e32 v73, v76, v73
	v_add_f32_e32 v73, v78, v73
	v_cndmask_b32_e32 v79, 0, v151, vcc
	v_cmp_lt_f32_e32 vcc, s70, v80
	v_sub_f32_e32 v151, v82, v146
	v_mul_f32_e32 v151, 0x3fb8aa3b, v151
	v_cndmask_b32_e32 v80, 0, v155, vcc
	v_sub_f32_e32 v155, v83, v146
	v_exp_f32_e32 v151, v151
	v_mul_f32_e32 v155, 0x3fb8aa3b, v155
	v_exp_f32_e32 v155, v155
	v_cmp_lt_f32_e32 vcc, s70, v82
	v_add_f32_e32 v73, v79, v73
	v_add_f32_e32 v73, v80, v73
	v_cndmask_b32_e32 v82, 0, v151, vcc
	v_cmp_lt_f32_e32 vcc, s70, v83
	v_sub_f32_e32 v151, v109, v146
	v_mul_f32_e32 v151, 0x3fb8aa3b, v151
	v_cndmask_b32_e32 v83, 0, v155, vcc
	v_sub_f32_e32 v155, v56, v146
	v_exp_f32_e32 v151, v151
	v_mul_f32_e32 v155, 0x3fb8aa3b, v155
	v_exp_f32_e32 v155, v155
	v_add_f32_e32 v73, v82, v73
	v_cmp_lt_f32_e32 vcc, s70, v109
	v_add_f32_e32 v73, v83, v73
	v_cvt_pk_bf16_f32 v53, v61, s0
	v_cndmask_b32_e32 v109, 0, v151, vcc
	v_cmp_lt_f32_e32 vcc, s70, v56
	v_add_f32_e32 v73, v109, v73
	v_mul_f32_e32 v159, 0x3fb8aa3b, v159
	v_cndmask_b32_e32 v56, 0, v155, vcc
	v_add_f32_e32 v73, v56, v73
	v_mov_b32_e32 v151, v73
	ds_write_b16 v142, v53 offset:96
	v_cvt_pk_bf16_f32 v53, v62, s0
	v_mov_b32_dpp v151, v151 quad_perm:[1,0,3,2] row_mask:0xf bank_mask:0xf
	v_add_f32_e32 v73, v73, v151
	v_mov_b32_e32 v151, v73
	v_exp_f32_e32 v159, v159
	ds_write_b16 v142, v53 offset:128
	v_mov_b32_dpp v151, v151 quad_perm:[2,3,0,1] row_mask:0xf bank_mask:0xf
	v_add_f32_e32 v73, v73, v151
	v_mov_b32_e32 v151, v73
	v_cvt_pk_bf16_f32 v53, v63, s0
	ds_write_b16 v142, v53 offset:160
	v_mov_b32_dpp v151, v151 row_half_mirror row_mask:0xf bank_mask:0xf
	v_add_f32_e32 v151, v73, v151
	v_sub_f32_e32 v73, v72, v145
	v_mul_f32_e32 v73, 0x3fb8aa3b, v73
	v_exp_f32_e32 v73, v73
	v_cvt_pk_bf16_f32 v53, v64, s0
	v_cmp_lt_f32_e32 vcc, s70, v72
	v_sub_f32_e32 v160, v81, v145
	ds_write_b16 v142, v53 offset:192
	v_cvt_pk_bf16_f32 v53, v65, s0
	v_cndmask_b32_e32 v72, 0, v73, vcc
	v_mul_f32_e32 v160, 0x3fb8aa3b, v160
	v_cmp_lt_f32_e32 vcc, s70, v77
	ds_write_b16 v142, v53 offset:224
	v_cvt_pk_bf16_f32 v53, v54, s0
	v_exp_f32_e32 v160, v160
	v_cndmask_b32_e32 v77, 0, v159, vcc
	v_sub_f32_e32 v159, v152, v145
	ds_write_b16 v142, v53 offset:256
	ds_write_b16 v142, v85 offset:288
	v_cvt_pk_bf16_f32 v53, v58, s0
	v_mul_f32_e32 v159, 0x3fb8aa3b, v159
	ds_write_b16 v142, v53 offset:336
	v_cvt_pk_bf16_f32 v53, v67, s0
	v_exp_f32_e32 v159, v159
	ds_write_b16 v142, v53 offset:368
	v_cvt_pk_bf16_f32 v53, v68, s0
	v_cmp_lt_f32_e32 vcc, s70, v81
	ds_write_b16 v142, v53 offset:400
	v_cvt_pk_bf16_f32 v53, v69, s0
	v_cndmask_b32_e32 v81, 0, v160, vcc
	v_sub_f32_e32 v160, v153, v145
	ds_write_b16 v142, v53 offset:432
	v_cvt_pk_bf16_f32 v53, v70, s0
	v_mul_f32_e32 v160, 0x3fb8aa3b, v160
	v_cmp_lt_f32_e32 vcc, s70, v152
	v_sub_f32_e32 v152, v156, v145
	ds_write_b16 v142, v53 offset:464
	v_cvt_pk_bf16_f32 v53, v71, s0
	v_exp_f32_e32 v160, v160
	v_cndmask_b32_e32 v159, 0, v159, vcc
	v_cmp_lt_f32_e32 vcc, s70, v153
	v_mul_f32_e32 v152, 0x3fb8aa3b, v152
	v_sub_f32_e32 v153, v157, v145
	ds_write_b16 v142, v53 offset:496
	v_cvt_pk_bf16_f32 v53, v74, s0
	v_exp_f32_e32 v152, v152
	v_mul_f32_e32 v153, 0x3fb8aa3b, v153
	ds_write_b16 v142, v53 offset:528
	v_cvt_pk_bf16_f32 v53, v75, s0
	v_exp_f32_e32 v153, v153
	ds_write_b16 v142, v53 offset:560
	v_cvt_pk_bf16_f32 v53, v55, s0
	ds_write_b16 v142, v53 offset:592
	ds_write_b16 v142, v85 offset:624
	v_cvt_pk_bf16_f32 v53, v66, s0
	v_cndmask_b32_e32 v160, 0, v160, vcc
	v_cmp_lt_f32_e32 vcc, s70, v156
	ds_write_b16 v142, v53 offset:672
	v_cvt_pk_bf16_f32 v53, v76, s0
	v_add_f32_e32 v73, 0, v72
	v_cndmask_b32_e32 v156, 0, v152, vcc
	v_cmp_lt_f32_e32 vcc, s70, v157
	v_sub_f32_e32 v152, v158, v145
	ds_write_b16 v142, v53 offset:704
	v_cvt_pk_bf16_f32 v53, v78, s0
	v_add_f32_e32 v73, v77, v73
	v_cndmask_b32_e32 v157, 0, v153, vcc
	v_mul_f32_e32 v152, 0x3fb8aa3b, v152
	v_sub_f32_e32 v153, v57, v145
	ds_write_b16 v142, v53 offset:736
	v_cvt_pk_bf16_f32 v53, v79, s0
	v_add_f32_e32 v73, v81, v73
	v_exp_f32_e32 v152, v152
	v_mul_f32_e32 v153, 0x3fb8aa3b, v153
	ds_write_b16 v142, v53 offset:768
	v_cvt_pk_bf16_f32 v53, v80, s0
	v_add_f32_e32 v73, v159, v73
	v_exp_f32_e32 v153, v153
	ds_write_b16 v142, v53 offset:800
	v_cvt_pk_bf16_f32 v53, v82, s0
	v_add_f32_e32 v73, v160, v73
	ds_write_b16 v142, v53 offset:832
	v_cvt_pk_bf16_f32 v53, v83, s0
	v_add_f32_e32 v73, v156, v73
	v_cmp_lt_f32_e32 vcc, s70, v158
	ds_write_b16 v142, v53 offset:864
	v_cvt_pk_bf16_f32 v53, v109, s0
	v_add_f32_e32 v73, v157, v73
	v_cndmask_b32_e32 v158, 0, v152, vcc
	v_cmp_lt_f32_e32 vcc, s70, v57
	ds_write_b16 v142, v53 offset:896
	v_cvt_pk_bf16_f32 v53, v56, s0
	v_add_f32_e32 v73, v158, v73
	v_cndmask_b32_e32 v57, 0, v153, vcc
	ds_write_b16 v142, v53 offset:928
	ds_write_b16 v142, v85 offset:960
	v_cvt_pk_bf16_f32 v53, v72, s0
	v_add_f32_e32 v73, v57, v73
	ds_write_b16 v142, v53 offset:1008
	v_cvt_pk_bf16_f32 v53, v77, s0
	v_mov_b32_e32 v152, v73
	ds_write_b16 v142, v53 offset:1040
	v_cvt_pk_bf16_f32 v53, v81, s0
	v_mov_b32_dpp v152, v152 quad_perm:[1,0,3,2] row_mask:0xf bank_mask:0xf
	ds_write_b16 v142, v53 offset:1072
	v_cvt_pk_bf16_f32 v53, v159, s0
	v_add_f32_e32 v73, v73, v152
	ds_write_b16 v142, v53 offset:1104
	v_cvt_pk_bf16_f32 v53, v160, s0
	v_mov_b32_e32 v152, v73
	ds_write_b16 v142, v53 offset:1136
	v_cvt_pk_bf16_f32 v53, v156, s0
	v_mov_b32_dpp v152, v152 quad_perm:[2,3,0,1] row_mask:0xf bank_mask:0xf
	ds_write_b16 v142, v53 offset:1168
	v_cvt_pk_bf16_f32 v53, v157, s0
	v_add_f32_e32 v73, v73, v152
	ds_write_b16 v142, v53 offset:1200
	v_cvt_pk_bf16_f32 v53, v158, s0
	v_mov_b32_e32 v152, v73
	ds_write_b16 v142, v53 offset:1232
	v_cvt_pk_bf16_f32 v53, v57, s0
	v_mov_b32_dpp v152, v152 row_half_mirror row_mask:0xf bank_mask:0xf
	ds_write_b16 v142, v53 offset:1264
	ds_write_b16 v142, v85 offset:1296
	v_add_f32_e32 v152, v73, v152
	s_waitcnt lgkmcnt(0)
	v_mov_b32_e32 v154, v150
	v_mov_b32_e32 v155, v151
	v_mov_b32_e32 v153, v152
	v_mov_b32_dpp v154, v154 row_mirror row_mask:0xf bank_mask:0xf
	v_mov_b32_dpp v155, v155 row_mirror row_mask:0xf bank_mask:0xf
	v_mov_b32_dpp v153, v153 row_mirror row_mask:0xf bank_mask:0xf
	s_setprio 1
	ds_read_b128 v[54:57], v144
	v_add_u32_e32 v52, v52, v140
	v_lshl_add_u32 v109, v52, 1, v143
	v_add_u32_e32 v52, 0xcc00, v109
	v_add_u32_e32 v82, 0xcc40, v109
	ds_read_b128 v[58:61], v109 offset:52224
	ds_read_b128 v[62:65], v144 offset:64
	ds_read_b128 v[156:159], v144 offset:256
	ds_read_b128 v[66:69], v109 offset:59136
	ds_read_b128 v[70:73], v109 offset:59200
	ds_read_b128 v[74:77], v52 offset:13824
	ds_read_b128 v[78:81], v52 offset:20736
	ds_read_b128 v[160:163], v52 offset:27648
	ds_read_b128 v[164:167], v82 offset:34560
	ds_read_b128 v[168:171], v52 offset:34560
	ds_read_b128 v[172:175], v109 offset:59392
	ds_read_b128 v[176:179], v52 offset:41472
	ds_read_b128 v[180:183], v52 offset:48384
	s_waitcnt lgkmcnt(12)
	v_mfma_f32_16x16x32_bf16 v[58:61], v[54:57], v[58:61], 0
	v_add_u32_e32 v192, 0xcc80, v109
	v_add_u32_e32 v193, 0xccc0, v109
	s_waitcnt lgkmcnt(9)
	v_mfma_f32_16x16x32_bf16 v[66:69], v[54:57], v[66:69], 0
	s_waitcnt lgkmcnt(7)
	v_mfma_f32_16x16x32_bf16 v[74:77], v[54:57], v[74:77], 0
	s_waitcnt lgkmcnt(6)
	v_mfma_f32_16x16x32_bf16 v[78:81], v[54:57], v[78:81], 0
	s_waitcnt lgkmcnt(5)
	v_mfma_f32_16x16x32_bf16 v[160:163], v[54:57], v[160:163], 0
	s_waitcnt lgkmcnt(3)
	v_mfma_f32_16x16x32_bf16 v[168:171], v[54:57], v[168:171], 0
	s_waitcnt lgkmcnt(1)
	v_mfma_f32_16x16x32_bf16 v[176:179], v[54:57], v[176:179], 0
	s_waitcnt lgkmcnt(0)
	v_mfma_f32_16x16x32_bf16 v[52:55], v[54:57], v[180:183], 0
	ds_read_b128 v[180:183], v109 offset:52288
	ds_read_b128 v[184:187], v109 offset:52352
	s_waitcnt lgkmcnt(1)
	v_mfma_f32_16x16x32_bf16 v[56:59], v[62:65], v[180:183], v[58:61]
	v_mfma_f32_16x16x32_bf16 v[66:69], v[62:65], v[70:73], v[66:69]
	ds_read_b128 v[70:73], v82 offset:13824
	ds_read_b128 v[180:183], v82 offset:20736
	s_waitcnt lgkmcnt(1)
	v_mfma_f32_16x16x32_bf16 v[70:73], v[62:65], v[70:73], v[74:77]
	s_waitcnt lgkmcnt(0)
	v_mfma_f32_16x16x32_bf16 v[74:77], v[62:65], v[180:183], v[78:81]
	ds_read_b128 v[180:183], v192 offset:34560
	s_nop 1
	ds_read_b128 v[78:81], v82 offset:27648
	s_waitcnt lgkmcnt(0)
	v_mfma_f32_16x16x32_bf16 v[78:81], v[62:65], v[78:81], v[160:163]
	v_mfma_f32_16x16x32_bf16 v[160:163], v[62:65], v[164:167], v[168:171]
	ds_read_b128 v[164:167], v82 offset:41472
	s_nop 1
	ds_read_b128 v[168:171], v82 offset:48384
	s_waitcnt lgkmcnt(1)
	v_mfma_f32_16x16x32_bf16 v[164:167], v[62:65], v[164:167], v[176:179]
	s_waitcnt lgkmcnt(0)
	v_mfma_f32_16x16x32_bf16 v[52:55], v[62:65], v[168:171], v[52:55]
	ds_read_b128 v[60:63], v144 offset:128
	ds_read_b128 v[168:171], v144 offset:192
	s_waitcnt lgkmcnt(1)
	v_mfma_f32_16x16x32_bf16 v[56:59], v[60:63], v[184:187], v[56:59]
	ds_read_b128 v[176:179], v109 offset:59264
	ds_read_b128 v[184:187], v109 offset:59328
	s_waitcnt lgkmcnt(1)
	v_mfma_f32_16x16x32_bf16 v[64:67], v[60:63], v[176:179], v[66:69]
	ds_read_b128 v[176:179], v192 offset:13824
	ds_read_b128 v[188:191], v192 offset:20736
	s_waitcnt lgkmcnt(1)
	v_mfma_f32_16x16x32_bf16 v[68:71], v[60:63], v[176:179], v[70:73]
	ds_read_b128 v[176:179], v192 offset:27648
	s_waitcnt lgkmcnt(1)
	v_mfma_f32_16x16x32_bf16 v[72:75], v[60:63], v[188:191], v[74:77]
	ds_read_b128 v[188:191], v193 offset:34560
	s_waitcnt lgkmcnt(1)
	v_mfma_f32_16x16x32_bf16 v[76:79], v[60:63], v[176:179], v[78:81]
	v_mfma_f32_16x16x32_bf16 v[80:83], v[60:63], v[180:183], v[160:163]
	s_nop 2
	ds_read_b128 v[160:163], v192 offset:41472
	ds_read_b128 v[176:179], v192 offset:48384
	s_waitcnt lgkmcnt(1)
	v_mfma_f32_16x16x32_bf16 v[160:163], v[60:63], v[160:163], v[164:167]
	s_waitcnt lgkmcnt(0)
	v_mfma_f32_16x16x32_bf16 v[52:55], v[60:63], v[176:179], v[52:55]
	ds_read_b128 v[60:63], v109 offset:52416
	ds_read_b128 v[164:167], v109 offset:52480
	v_add_u32_e32 v109, 0xcd00, v109
	s_waitcnt lgkmcnt(1)
	v_mfma_f32_16x16x32_bf16 v[56:59], v[168:171], v[60:63], v[56:59]
	v_mfma_f32_16x16x32_bf16 v[60:63], v[168:171], v[184:187], v[64:67]
	s_nop 2
	ds_read_b128 v[64:67], v193 offset:13824
	ds_read_b128 v[176:179], v193 offset:20736
	s_waitcnt lgkmcnt(1)
	v_mfma_f32_16x16x32_bf16 v[64:67], v[168:171], v[64:67], v[68:71]
	s_waitcnt lgkmcnt(0)
	v_mfma_f32_16x16x32_bf16 v[68:71], v[168:171], v[176:179], v[72:75]
	ds_read_b128 v[176:179], v109 offset:34560
	s_nop 1
	ds_read_b128 v[72:75], v193 offset:27648
	s_waitcnt lgkmcnt(0)
	v_mfma_f32_16x16x32_bf16 v[180:183], v[168:171], v[72:75], v[76:79]
	ds_read_b128 v[72:75], v193 offset:41472
	s_nop 1
	ds_read_b128 v[76:79], v193 offset:48384
	v_mfma_f32_16x16x32_bf16 v[184:187], v[168:171], v[188:191], v[80:83]
	s_waitcnt lgkmcnt(1)
	v_mfma_f32_16x16x32_bf16 v[160:163], v[168:171], v[72:75], v[160:163]
	v_mfma_f32_16x16x32_bf16 v[80:83], v[156:159], v[164:167], v[56:59]
	v_mfma_f32_16x16x32_bf16 v[72:75], v[156:159], v[172:175], v[60:63]
	s_nop 1
	ds_read_b128 v[56:59], v109 offset:13824
	ds_read_b128 v[60:63], v109 offset:20736
	s_waitcnt lgkmcnt(2)
	v_mfma_f32_16x16x32_bf16 v[52:55], v[168:171], v[76:79], v[52:55]
	s_waitcnt lgkmcnt(1)
	v_mfma_f32_16x16x32_bf16 v[76:79], v[156:159], v[56:59], v[64:67]
	ds_read_b128 v[56:59], v109 offset:27648
	s_waitcnt lgkmcnt(1)
	v_mfma_f32_16x16x32_bf16 v[68:71], v[156:159], v[60:63], v[68:71]
	ds_read_b128 v[60:63], v109 offset:41472
	ds_read_b128 v[164:167], v109 offset:48384
	s_waitcnt lgkmcnt(2)
	v_mfma_f32_16x16x32_bf16 v[64:67], v[156:159], v[56:59], v[180:183]
	v_mfma_f32_16x16x32_bf16 v[56:59], v[156:159], v[176:179], v[184:187]
	s_waitcnt lgkmcnt(1)
	v_mfma_f32_16x16x32_bf16 v[60:63], v[156:159], v[60:63], v[160:163]
	s_waitcnt lgkmcnt(0)
	v_mfma_f32_16x16x32_bf16 v[52:55], v[156:159], v[164:167], v[52:55]
	s_setprio 0
	v_div_scale_f32 v109, s[38:39], v149, v149, 1.0
	v_rcp_f32_e32 v157, v109
	v_or_b32_e32 v156, v108, v141
	v_lshlrev_b32_e32 v108, s0, v156
	v_add_u32_e32 v108, s76, v108
	v_fma_f32 v158, -v109, v157, 1.0
	v_fmac_f32_e32 v157, v158, v157
	v_div_scale_f32 v158, vcc, 1.0, v149, 1.0
	v_mul_f32_e32 v159, v158, v157
	v_fma_f32 v160, -v109, v159, v158
	v_fmac_f32_e32 v159, v160, v157
	v_fma_f32 v109, -v109, v159, v158
	v_div_fmas_f32 v109, v109, v157, v159
	v_div_fixup_f32 v157, v109, v149, 1.0
	v_ashrrev_i32_e32 v109, 31, v108
	v_lshlrev_b64 v[158:159], 13, v[108:109]
	v_mul_f32_e32 v72, v157, v72
	v_mul_f32_e32 v56, v157, v56
	v_lshl_add_u64 v[158:159], v[104:105], 0, v[158:159]
	v_cvt_pk_bf16_f32 v72, v72, s0
	v_cvt_pk_bf16_f32 v56, v56, s0
	v_mul_f32_e32 v80, v157, v80
	global_store_short v[158:159], v72, off offset:32
	v_mul_f32_e32 v72, v157, v76
	v_mul_f32_e32 v68, v157, v68
	v_mul_f32_e32 v64, v157, v64
	global_store_short v[158:159], v56, off offset:160
	v_mul_f32_e32 v56, v157, v60
	v_mul_f32_e32 v52, v157, v52
	v_cvt_pk_bf16_f32 v80, v80, s0
	v_cvt_pk_bf16_f32 v72, v72, s0
	v_cvt_pk_bf16_f32 v68, v68, s0
	v_cvt_pk_bf16_f32 v64, v64, s0
	v_cvt_pk_bf16_f32 v56, v56, s0
	v_cvt_pk_bf16_f32 v52, v52, s0
	global_store_short v[158:159], v80, off
	global_store_short v[158:159], v72, off offset:64
	global_store_short v[158:159], v68, off offset:96
	global_store_short v[158:159], v64, off offset:128
	global_store_short v[158:159], v56, off offset:192
	global_store_short v[158:159], v52, off offset:224
	s_and_saveexec_b64 s[38:39], s[16:17]
	s_cbranch_execz .LBB0_1753
	v_cmp_gt_f32_e32 vcc, s71, v149
	v_lshlrev_b64 v[108:109], 7, v[108:109]
	v_lshl_add_u64 v[108:109], v[106:107], 0, v[108:109]
	v_cndmask_b32_e64 v52, 0, 32, vcc
	v_ldexp_f32 v52, v149, v52
	v_log_f32_e32 v52, v52
	v_cndmask_b32_e32 v56, 0, v137, vcc
	v_mul_f32_e32 v60, 0x3f317217, v52
	v_fma_f32 v60, v52, s72, -v60
	v_fmac_f32_e32 v60, 0x3377d1cf, v52
	v_fmac_f32_e32 v60, 0x3f317217, v52
	v_cmp_lt_f32_e64 vcc, |v52|, s73
	s_nop 1
	v_cndmask_b32_e32 v52, v52, v60, vcc
	v_sub_f32_e32 v52, v52, v56
	v_add_f32_e32 v52, v148, v52
	global_store_dword v[108:109], v52, off
